# prompt attention rewritten by hand: one unit covers both value halves (A waves QK+softmax+PV cols 0-63, B waves PV cols 64-127 from P in LDS), O1 kept in registers, combine via LDS stage
# speedup vs baseline: 1.0530x; 1.0146x over previous
; template<int THRL,bool PART> __device__ __forceinline__ int attn_unit(const bf16*Qb,const bf16*__restrict__ Kh,const bf16*__restrict__ Vh,bf16*Ob,const int NT,const int vlim_in,char*shm,const int s0,const bool primed,const bf16*nKh,const bf16*nVh,bf16*fuseM,const float lam){
;   int tid=threadIdx.x; asm volatile("":"+v"(tid));
;   const int lane=tid&63,r32=lane&31,hi=lane>>5; const int wid=__builtin_amdgcn_readfirstlane(tid>>6);
;   const int vlim=(vlim_in<0)?(wid>>1):vlim_in;
;   const bool act=PART?(wid<2):true;
;   const bf16*Qw=Qb+(long)(wid*QBLK)*KP;
;   const unsigned lds0=(unsigned)(uintptr_t)shm;
;   float*wsf=(float*)(shm+LDS_WS)+wid*64;
;   const bf16*ksrc=Kh+(long)lane*KP+wid*8;
;   const bf16*vsrc=Vh+(long)(16*(wid&3)+(lane>>2))*KP+(wid>>2)*32+(lane&3)*8;
;   const unsigned kdst=lds0+LDS_K+wid*1024, vdst=lds0+LDS_V+wid*1024;
; __global__ void __launch_bounds__(NWAVES * 64, 2) mk_fwd(Args args) {
;     ...
;         for (int v = vcu; v < 256; v += G) {
;             const int bh = v >> 3, s = v & 7, b = bh >> 2, hd = bh & 3;
;             int ring0 = 0; bool primed = false;
;             for (int i = 0; i < 8; ++i) { const int qb = (i >> 2) ? 15 - s : s, j = (i >> 1) & 1, vh = i & 1;
;                 const bf16* Qp = Qb + (size_t)(b * 4096 + qb * 256) * 512 + (hd * 2 + j) * 64; const bf16* Kp = Kb + (size_t)(b * 4096) * 512 + (hd * 2 + j) * 64; const bf16* Vp = Vb + (size_t)(b * 4096) * 512 + (hd * 2 + vh) * 64;
;                 bf16* Op = ATTO + (size_t)(b * 4096 + qb * 256) * 1024 + ((hd * 2 + j) * 2 + vh) * 64;
;                 bf16* Mp = ((i & 3) == 3) ? H + (size_t)(b * 4096 + qb * 256) * 1024 + 512 + hd * 128 : nullptr;
;                 const bool more = i < 7; const int jn = ((i + 1) >> 1) & 1, vn = (i + 1) & 1;
;                 const bf16* nK = Kb + (size_t)(b * 4096) * 512 + (hd * 2 + jn) * 64; const bf16* nV = Vb + (size_t)(b * 4096) * 512 + (hd * 2 + vn) * 64;
;                 ring0 = attn_body::attn_unit<8, false>((const attn_body::bf16*)Qp, (const attn_body::bf16*)Kp, (const attn_body::bf16*)Vp, (attn_body::bf16*)Op, 4 * (qb + 1), -1, (char*)lds, ring0, primed,
;                                                        more ? (const attn_body::bf16*)nK : nullptr, more ? (const attn_body::bf16*)nV : nullptr, (attn_body::bf16*)Mp, lam); primed = more; }
.LBB0_925:
	s_cmpk_gt_i32 s92, 0xff
	s_waitcnt vmcnt(0) lgkmcnt(0)
	s_barrier
	s_cbranch_scc1 .LBB0_1021
	v_mov_b32_e32 v3, 0x1a0000
	global_load_dword v216, v3, s[66:67]
	v_and_b32_e32 v0, 63, v252
	v_and_b32_e32 v1, 31, v252
	v_bfe_u32 v2, v252, 5, 1
	v_lshrrev_b32_e32 v3, 6, v252
	s_nop 0
	v_readfirstlane_b32 s4, v3
	s_and_b32 s5, s4, 3
	s_lshr_b32 s6, s4, 2
	s_mov_b32 s48, 0x41000000
	v_lshlrev_b32_e32 v232, 10, v2
	v_lshl_add_u32 v232, v1, 4, v232
	v_bfe_u32 v217, v0, 4, 1
	v_lshlrev_b32_e32 v233, 5, v217
	v_and_b32_e32 v217, 3, v0
	v_lshl_add_u32 v233, v217, 3, v233
	v_bfe_u32 v217, v0, 2, 2
	v_lshl_add_u32 v217, v2, 2, v217
	v_lshl_add_u32 v233, v217, 6, v233
	s_lshl_b32 s34, s6, 13
	v_add_u32_e32 v233, s34, v233
	s_lshl_b32 s34, s5, 12
	s_add_i32 s34, s34, 0x16000
	v_lshlrev_b32_e32 v234, 4, v0
	v_add_u32_e32 v234, s34, v234
	s_lshl_b32 s34, s5, 10
	s_add_i32 s34, s34, 0x1e000
	v_mov_b32_e32 v235, s34
	v_lshlrev_b32_e32 v240, 2, v1
	v_lshlrev_b32_e32 v241, 4, v2
	s_lshl_b32 s34, s4, 4
	v_lshlrev_b32_e32 v236, 10, v0
	v_add_u32_e32 v236, s34, v236
	v_lshrrev_b32_e32 v217, 2, v0
	v_lshlrev_b32_e32 v237, 10, v217
	v_and_b32_e32 v217, 3, v0
	v_lshl_add_u32 v237, v217, 4, v237
	s_lshl_b32 s34, s5, 14
	s_lshr_b32 s35, s4, 2
	s_lshl_b32 s35, s35, 6
	s_add_i32 s34, s34, s35
	v_add_u32_e32 v237, s34, v237
	v_add_u32_e32 v238, 0x80, v237
	v_lshlrev_b32_e32 v239, 10, v1
	v_lshl_add_u32 v239, v2, 4, v239
	s_waitcnt vmcnt(0)
	v_readfirstlane_b32 s7, v216
	s_mov_b32 s8, s92
.Lat_v:
	s_lshr_b32 s9, s8, 5
	s_bfe_u32 s10, s8, 0x20003
	s_and_b32 s11, s8, 7
	s_mov_b32 s12, 0
.Lat_blk:
	s_lshl_b32 s13, s11, 1
	s_sub_i32 s34, 30, s13
	s_bitcmp1_b32 s12, 1
	s_cselect_b32 s13, s34, s13
	s_and_b32 s34, s12, 1
	s_add_i32 s13, s13, s34
	s_lshl_b32 s15, s13, 1
	s_add_i32 s15, s15, 2
	s_lshr_b32 s34, s5, 1
	s_xor_b32 s34, s34, 1
	s_sub_i32 s16, s15, s34
	s_mov_b32 s14, 0
.Lat_j:
	s_lshl_b32 s34, s10, 1
	s_add_i32 s34, s34, s14
	s_add_u32 s18, s66, 0xf300000
	s_addc_u32 s19, s67, 0
	s_lshl_b32 s36, s9, 22
	s_add_u32 s18, s18, s36
	s_addc_u32 s19, s19, 0
	s_lshl_b32 s36, s34, 7
	s_add_u32 s18, s18, s36
	s_addc_u32 s19, s19, 0
	s_add_u32 s20, s66, 0x12200000
	s_addc_u32 s21, s67, 0
	s_lshl_b32 s36, s9, 22
	s_add_u32 s20, s20, s36
	s_addc_u32 s21, s21, 0
	s_lshl_b32 s36, s10, 8
	s_add_u32 s20, s20, s36
	s_addc_u32 s21, s21, 0
	s_add_u32 s22, s66, 0xd100000
	s_addc_u32 s23, s67, 0
	s_lshl_b32 s36, s9, 22
	s_add_u32 s22, s22, s36
	s_addc_u32 s23, s23, 0
	s_lshl_b32 s36, s13, 17
	s_add_u32 s22, s22, s36
	s_addc_u32 s23, s23, 0
	s_lshl_b32 s36, s5, 15
	s_add_u32 s22, s22, s36
	s_addc_u32 s23, s23, 0
	s_lshl_b32 s36, s34, 7
	s_add_u32 s22, s22, s36
	s_addc_u32 s23, s23, 0
	s_mov_b32 s17, 0
	s_mov_b32 s24, 0
	s_mov_b32 s25, 0
	s_mov_b32 s27, 0
	s_mov_b32 s30, 0x6000
	s_lshl_b32 s37, s4, 10
	s_add_i32 s38, s37, s27
	s_mov_b32 m0, s38
	s_nop 0
	global_load_lds_dwordx4 v236, s[18:19]
	s_add_i32 s38, s37, s30
	s_mov_b32 m0, s38
	s_nop 0
	global_load_lds_dwordx4 v237, s[20:21]
	s_add_i32 m0, s38, 0x2000
	s_nop 0
	global_load_lds_dwordx4 v238, s[20:21]
	s_add_u32 s18, s18, 0x10000
	s_addc_u32 s19, s19, 0
	s_add_u32 s20, s20, 0x10000
	s_addc_u32 s21, s21, 0
	s_mov_b32 s27, 0x2000
	s_mov_b32 s30, 0xa000
	s_lshl_b32 s37, s4, 10
	s_add_i32 s38, s37, s27
	s_mov_b32 m0, s38
	s_nop 0
	global_load_lds_dwordx4 v236, s[18:19]
	s_add_i32 s38, s37, s30
	s_mov_b32 m0, s38
	s_nop 0
	global_load_lds_dwordx4 v237, s[20:21]
	s_add_i32 m0, s38, 0x2000
	s_nop 0
	global_load_lds_dwordx4 v238, s[20:21]
	s_add_u32 s18, s18, 0x10000
	s_addc_u32 s19, s19, 0
	s_add_u32 s20, s20, 0x10000
	s_addc_u32 s21, s21, 0
	s_cmp_lg_u32 s6, 0
	s_cbranch_scc1 .Lat_noq
	global_load_dwordx4 v[4:7], v239, s[22:23]
	global_load_dwordx4 v[8:11], v239, s[22:23] offset:32
	global_load_dwordx4 v[12:15], v239, s[22:23] offset:64
	global_load_dwordx4 v[16:19], v239, s[22:23] offset:96
.Lat_noq:
	v_mov_b32_e32 v148, 0
	v_mov_b32_e32 v149, 0
	v_mov_b32_e32 v150, 0
	v_mov_b32_e32 v151, 0
	v_mov_b32_e32 v152, 0
	v_mov_b32_e32 v153, 0
	v_mov_b32_e32 v154, 0
	v_mov_b32_e32 v155, 0
	v_mov_b32_e32 v156, 0
	v_mov_b32_e32 v157, 0
	v_mov_b32_e32 v158, 0
	v_mov_b32_e32 v159, 0
	v_mov_b32_e32 v160, 0
	v_mov_b32_e32 v161, 0
	v_mov_b32_e32 v162, 0
	v_mov_b32_e32 v163, 0
	v_mov_b32_e32 v164, 0
	v_mov_b32_e32 v165, 0
	v_mov_b32_e32 v166, 0
	v_mov_b32_e32 v167, 0
	v_mov_b32_e32 v168, 0
	v_mov_b32_e32 v169, 0
	v_mov_b32_e32 v170, 0
	v_mov_b32_e32 v171, 0
	v_mov_b32_e32 v172, 0
	v_mov_b32_e32 v173, 0
	v_mov_b32_e32 v174, 0
	v_mov_b32_e32 v175, 0
	v_mov_b32_e32 v176, 0
	v_mov_b32_e32 v177, 0
	v_mov_b32_e32 v178, 0
	v_mov_b32_e32 v179, 0
	v_mov_b32_e32 v84, 0
	v_mov_b32_e32 v85, 0
	v_mov_b32_e32 v86, 0
	v_mov_b32_e32 v87, 0
	v_mov_b32_e32 v88, 0
	v_mov_b32_e32 v89, 0
	v_mov_b32_e32 v90, 0
	v_mov_b32_e32 v91, 0
	v_mov_b32_e32 v92, 0
	v_mov_b32_e32 v93, 0
	v_mov_b32_e32 v94, 0
	v_mov_b32_e32 v95, 0
	v_mov_b32_e32 v96, 0
	v_mov_b32_e32 v97, 0
	v_mov_b32_e32 v98, 0
	v_mov_b32_e32 v99, 0
	v_mov_b32_e32 v212, 0
	v_mov_b32_e32 v213, 0
	s_waitcnt vmcnt(0)
	s_barrier
; __device__ __forceinline__ float max3f(float a,float b,float c){float r;asm("v_max3_f32 %0, %1, %2, %3":"=v"(r):"v"(a),"v"(b),"v"(c));return r;}
; __device__ __forceinline__ void qkt(f32x16&p0,f32x16&p1,const char*Kslot,const bf16x8*qr,const f32x16&negm,int r32,int hi){
;   const char*kb=Kslot+hi*1024+r32*16;
;   #pragma unroll
;   for(int d0=0;d0<4;++d0){
;     const bf16x8 b0=*reinterpret_cast<const bf16x8*>(kb+d0*2048);
;     const bf16x8 b1=*reinterpret_cast<const bf16x8*>(kb+d0*2048+512);
;     if(d0==0){p0=__builtin_amdgcn_mfma_f32_32x32x16_bf16(b0,qr[0],negm,0,0,0);p1=__builtin_amdgcn_mfma_f32_32x32x16_bf16(b1,qr[0],negm,0,0,0);}
;     else{p0=__builtin_amdgcn_mfma_f32_32x32x16_bf16(b0,qr[d0],p0,0,0,0);p1=__builtin_amdgcn_mfma_f32_32x32x16_bf16(b1,qr[d0],p1,0,0,0);}}
; }
; __device__ __forceinline__ void kload8(bf16x8*kf,lds_cptr kp){
;   kf[0]=*(const __attribute__((address_space(3))) bf16x8*)(kp);      kf[1]=*(const __attribute__((address_space(3))) bf16x8*)(kp+512);
;   kf[2]=*(const __attribute__((address_space(3))) bf16x8*)(kp+2048); kf[3]=*(const __attribute__((address_space(3))) bf16x8*)(kp+2560);
;   kf[4]=*(const __attribute__((address_space(3))) bf16x8*)(kp+4096); kf[5]=*(const __attribute__((address_space(3))) bf16x8*)(kp+4608);
;   kf[6]=*(const __attribute__((address_space(3))) bf16x8*)(kp+6144); kf[7]=*(const __attribute__((address_space(3))) bf16x8*)(kp+6656);
; }
; __device__ __forceinline__ void kload2(bf16x8*kf,lds_cptr kp,int j){ kf[2*j]=*(const __attribute__((address_space(3))) bf16x8*)(kp+j*2048); kf[2*j+1]=*(const __attribute__((address_space(3))) bf16x8*)(kp+j*2048+512); }
; __device__ __forceinline__ s16x4 vtr(lds_cptr p){ return __builtin_bit_cast(s16x4,__builtin_amdgcn_ds_read_tr16_b64_v4i16((__attribute__((address_space(3))) v4i16_t*)p)); }
; __device__ __forceinline__ float rowmax(const f32x16&p0,const f32x16&p1){
;   float a=max3f(p0[0],p0[1],p1[0]),b=max3f(p0[2],p0[3],p1[1]);a=max3f(a,p1[2],p1[3]);
;   #pragma unroll
;   for(int r=4;r<16;r+=4){a=max3f(a,p0[r],p0[r+1]);b=max3f(b,p0[r+2],p0[r+3]);a=max3f(a,p1[r],p1[r+1]);b=max3f(b,p1[r+2],p1[r+3]);}
;   const float m=max2f(a,b);
;   auto rr=__builtin_amdgcn_permlane32_swap(__float_as_uint(m),__float_as_uint(m),false,false);
;   return max2f(__uint_as_float(rr[0]),__uint_as_float(rr[1]));
.Lat_t:
	s_lshl_b32 s26, s24, 13
	s_add_i32 s34, s24, 2
	s_cmp_gt_u32 s34, 2
	s_cselect_b32 s35, 3, 0
	s_sub_i32 s34, s34, s35
	s_lshl_b32 s27, s34, 13
	s_lshl_b32 s28, s25, 14
	s_add_i32 s28, s28, 0x6000
	s_add_i32 s34, s25, 3
	s_and_b32 s34, s34, 3
	s_lshl_b32 s29, s34, 14
	s_add_i32 s29, s29, 0x6000
	s_add_i32 s34, s25, 2
	s_and_b32 s34, s34, 3
	s_lshl_b32 s30, s34, 14
	s_add_i32 s30, s30, 0x6000
	s_and_b32 s34, s17, 1
	s_lshl_b32 s31, s34, 14
	s_xor_b32 s32, s31, 0x4000
	s_lshl_b32 s39, s34, 7
	s_xor_b32 s40, s39, 0x80
	s_cmp_lg_u32 s6, 0
	s_cbranch_scc1 .Lat_B
	s_cmp_lt_u32 s17, s16
	s_cbranch_scc0 .Lat_Aend
	v_add_u32_e32 v216, s26, v232
	ds_read_b128 v[20:23], v216 offset:0
	ds_read_b128 v[24:27], v216 offset:512
	ds_read_b128 v[28:31], v216 offset:2048
	ds_read_b128 v[32:35], v216 offset:2560
	ds_read_b128 v[36:39], v216 offset:4096
	ds_read_b128 v[40:43], v216 offset:4608
	ds_read_b128 v[44:47], v216 offset:6144
	ds_read_b128 v[48:51], v216 offset:6656
	s_waitcnt lgkmcnt(6)
	v_mfma_f32_32x32x16_bf16 v[52:67], v[20:23], v[4:7], v[84:99]
	v_mfma_f32_32x32x16_bf16 v[68:83], v[24:27], v[4:7], v[84:99]
	s_waitcnt lgkmcnt(4)
	v_mfma_f32_32x32x16_bf16 v[52:67], v[28:31], v[8:11], v[52:67]
	v_mfma_f32_32x32x16_bf16 v[68:83], v[32:35], v[8:11], v[68:83]
	s_waitcnt lgkmcnt(2)
	v_mfma_f32_32x32x16_bf16 v[52:67], v[36:39], v[12:15], v[52:67]
	v_mfma_f32_32x32x16_bf16 v[68:83], v[40:43], v[12:15], v[68:83]
	s_waitcnt lgkmcnt(0)
	v_mfma_f32_32x32x16_bf16 v[52:67], v[44:47], v[16:19], v[52:67]
	v_mfma_f32_32x32x16_bf16 v[68:83], v[48:51], v[16:19], v[68:83]
	v_add_u32_e32 v216, s28, v233
	ds_read_b64_tr_b16 v[116:117], v216 offset:0
	ds_read_b64_tr_b16 v[118:119], v216 offset:512
	ds_read_b64_tr_b16 v[120:121], v216 offset:1024
	ds_read_b64_tr_b16 v[122:123], v216 offset:1536
	ds_read_b64_tr_b16 v[124:125], v216 offset:2048
	ds_read_b64_tr_b16 v[126:127], v216 offset:2560
	ds_read_b64_tr_b16 v[128:129], v216 offset:3072
	ds_read_b64_tr_b16 v[130:131], v216 offset:3584
	ds_read_b64_tr_b16 v[132:133], v216 offset:4096
	ds_read_b64_tr_b16 v[134:135], v216 offset:4608
	ds_read_b64_tr_b16 v[136:137], v216 offset:5120
	ds_read_b64_tr_b16 v[138:139], v216 offset:5632
	ds_read_b64_tr_b16 v[140:141], v216 offset:6144
	ds_read_b64_tr_b16 v[142:143], v216 offset:6656
	ds_read_b64_tr_b16 v[144:145], v216 offset:7168
	ds_read_b64_tr_b16 v[146:147], v216 offset:7680
	v_max3_f32 v218, v52, v53, v54
	v_max3_f32 v219, v55, v56, v57
	v_max3_f32 v218, v218, v58, v59
	v_max3_f32 v219, v219, v60, v61
	v_max3_f32 v218, v218, v62, v63
	v_max3_f32 v219, v219, v64, v65
	v_max3_f32 v218, v218, v66, v67
	v_max3_f32 v219, v219, v68, v69
	v_max3_f32 v218, v218, v70, v71
	v_max3_f32 v219, v219, v72, v73
	v_max3_f32 v218, v218, v74, v75
	v_max3_f32 v219, v219, v76, v77
	v_max3_f32 v218, v218, v78, v79
	v_max3_f32 v219, v219, v80, v81
	v_max3_f32 v218, v218, v82, v83
	v_max_f32_e32 v214, v218, v219
	v_mov_b32_e32 v218, v214
	s_nop 1
	v_permlane32_swap_b32_e32 v214, v218
	v_max_f32_e32 v214, v214, v218
	v_cmp_lt_f32_e32 vcc, s48, v214
	v_mov_b32_e32 v220, 0
	s_cmp_eq_u32 s17, 0
	s_cbranch_scc0 .Lat_chk
	v_mov_b32_e32 v212, v214
	v_sub_f32_e32 v52, v52, v214
	v_sub_f32_e32 v53, v53, v214
	v_sub_f32_e32 v54, v54, v214
	v_sub_f32_e32 v55, v55, v214
	v_sub_f32_e32 v56, v56, v214
	v_sub_f32_e32 v57, v57, v214
	v_sub_f32_e32 v58, v58, v214
	v_sub_f32_e32 v59, v59, v214
	v_sub_f32_e32 v60, v60, v214
	v_sub_f32_e32 v61, v61, v214
	v_sub_f32_e32 v62, v62, v214
	v_sub_f32_e32 v63, v63, v214
	v_sub_f32_e32 v64, v64, v214
	v_sub_f32_e32 v65, v65, v214
	v_sub_f32_e32 v66, v66, v214
	v_sub_f32_e32 v67, v67, v214
	v_sub_f32_e32 v68, v68, v214
	v_sub_f32_e32 v69, v69, v214
	v_sub_f32_e32 v70, v70, v214
	v_sub_f32_e32 v71, v71, v214
	v_sub_f32_e32 v72, v72, v214
	v_sub_f32_e32 v73, v73, v214
	v_sub_f32_e32 v74, v74, v214
	v_sub_f32_e32 v75, v75, v214
	v_sub_f32_e32 v76, v76, v214
	v_sub_f32_e32 v77, v77, v214
	v_sub_f32_e32 v78, v78, v214
	v_sub_f32_e32 v79, v79, v214
	v_sub_f32_e32 v80, v80, v214
	v_sub_f32_e32 v81, v81, v214
	v_sub_f32_e32 v82, v82, v214
	v_sub_f32_e32 v83, v83, v214
	v_xor_b32_e32 v84, 0x80000000, v212
	v_xor_b32_e32 v85, 0x80000000, v212
	v_xor_b32_e32 v86, 0x80000000, v212
	v_xor_b32_e32 v87, 0x80000000, v212
	v_xor_b32_e32 v88, 0x80000000, v212
	v_xor_b32_e32 v89, 0x80000000, v212
	v_xor_b32_e32 v90, 0x80000000, v212
	v_xor_b32_e32 v91, 0x80000000, v212
	v_xor_b32_e32 v92, 0x80000000, v212
	v_xor_b32_e32 v93, 0x80000000, v212
	v_xor_b32_e32 v94, 0x80000000, v212
	v_xor_b32_e32 v95, 0x80000000, v212
	v_xor_b32_e32 v96, 0x80000000, v212
	v_xor_b32_e32 v97, 0x80000000, v212
	v_xor_b32_e32 v98, 0x80000000, v212
	v_xor_b32_e32 v99, 0x80000000, v212
	s_branch .Lat_nores
.Lat_chk:
	s_cmp_lg_u64 vcc, 0
	s_cbranch_scc0 .Lat_nores
	v_max_f32_e32 v214, 0, v214
	v_add_f32_e32 v212, v212, v214
	v_sub_f32_e32 v52, v52, v214
	v_sub_f32_e32 v53, v53, v214
	v_sub_f32_e32 v54, v54, v214
	v_sub_f32_e32 v55, v55, v214
	v_sub_f32_e32 v56, v56, v214
	v_sub_f32_e32 v57, v57, v214
	v_sub_f32_e32 v58, v58, v214
	v_sub_f32_e32 v59, v59, v214
	v_sub_f32_e32 v60, v60, v214
	v_sub_f32_e32 v61, v61, v214
	v_sub_f32_e32 v62, v62, v214
	v_sub_f32_e32 v63, v63, v214
	v_sub_f32_e32 v64, v64, v214
	v_sub_f32_e32 v65, v65, v214
	v_sub_f32_e32 v66, v66, v214
	v_sub_f32_e32 v67, v67, v214
	v_sub_f32_e32 v68, v68, v214
	v_sub_f32_e32 v69, v69, v214
	v_sub_f32_e32 v70, v70, v214
	v_sub_f32_e32 v71, v71, v214
	v_sub_f32_e32 v72, v72, v214
	v_sub_f32_e32 v73, v73, v214
	v_sub_f32_e32 v74, v74, v214
	v_sub_f32_e32 v75, v75, v214
	v_sub_f32_e32 v76, v76, v214
	v_sub_f32_e32 v77, v77, v214
	v_sub_f32_e32 v78, v78, v214
	v_sub_f32_e32 v79, v79, v214
	v_sub_f32_e32 v80, v80, v214
	v_sub_f32_e32 v81, v81, v214
	v_sub_f32_e32 v82, v82, v214
	v_sub_f32_e32 v83, v83, v214
	v_xor_b32_e32 v84, 0x80000000, v212
	v_xor_b32_e32 v85, 0x80000000, v212
	v_xor_b32_e32 v86, 0x80000000, v212
	v_xor_b32_e32 v87, 0x80000000, v212
	v_xor_b32_e32 v88, 0x80000000, v212
	v_xor_b32_e32 v89, 0x80000000, v212
	v_xor_b32_e32 v90, 0x80000000, v212
	v_xor_b32_e32 v91, 0x80000000, v212
	v_xor_b32_e32 v92, 0x80000000, v212
	v_xor_b32_e32 v93, 0x80000000, v212
	v_xor_b32_e32 v94, 0x80000000, v212
	v_xor_b32_e32 v95, 0x80000000, v212
	v_xor_b32_e32 v96, 0x80000000, v212
	v_xor_b32_e32 v97, 0x80000000, v212
	v_xor_b32_e32 v98, 0x80000000, v212
	v_xor_b32_e32 v99, 0x80000000, v212
	v_exp_f32_e64 v215, -v214
	v_mov_b32_e32 v220, 1
	v_mul_f32_e32 v213, v213, v215
	v_add_u32_e32 v221, s39, v235
	v_add_u32_e32 v221, v221, v240
	ds_write_b32 v221, v215
	v_add_u32_e32 v221, s39, v235
	v_add_u32_e32 v221, v221, v241
	s_waitcnt lgkmcnt(0)
	ds_read_b128 v[20:23], v221 offset:0
	ds_read_b128 v[24:27], v221 offset:32
	ds_read_b128 v[28:31], v221 offset:64
	ds_read_b128 v[32:35], v221 offset:96
	s_waitcnt lgkmcnt(0)
	v_mul_f32_e32 v148, v148, v20
	v_mul_f32_e32 v149, v149, v21
	v_mul_f32_e32 v150, v150, v22
	v_mul_f32_e32 v151, v151, v23
	v_mul_f32_e32 v152, v152, v24
	v_mul_f32_e32 v153, v153, v25
	v_mul_f32_e32 v154, v154, v26
	v_mul_f32_e32 v155, v155, v27
	v_mul_f32_e32 v156, v156, v28
	v_mul_f32_e32 v157, v157, v29
	v_mul_f32_e32 v158, v158, v30
	v_mul_f32_e32 v159, v159, v31
	v_mul_f32_e32 v160, v160, v32
	v_mul_f32_e32 v161, v161, v33
	v_mul_f32_e32 v162, v162, v34
	v_mul_f32_e32 v163, v163, v35
	v_mul_f32_e32 v164, v164, v20
	v_mul_f32_e32 v165, v165, v21
	v_mul_f32_e32 v166, v166, v22
	v_mul_f32_e32 v167, v167, v23
	v_mul_f32_e32 v168, v168, v24
	v_mul_f32_e32 v169, v169, v25
	v_mul_f32_e32 v170, v170, v26
	v_mul_f32_e32 v171, v171, v27
	v_mul_f32_e32 v172, v172, v28
	v_mul_f32_e32 v173, v173, v29
	v_mul_f32_e32 v174, v174, v30
	v_mul_f32_e32 v175, v175, v31
	v_mul_f32_e32 v176, v176, v32
	v_mul_f32_e32 v177, v177, v33
	v_mul_f32_e32 v178, v178, v34
	v_mul_f32_e32 v179, v179, v35
.Lat_nores:
	s_lshr_b32 s41, s39, 5
	v_add_u32_e32 v221, s41, v235
	ds_write_b32 v221, v220 offset:256
	v_exp_f32_e32 v52, v52
	v_exp_f32_e32 v53, v53
	v_exp_f32_e32 v54, v54
	v_exp_f32_e32 v55, v55
	v_exp_f32_e32 v56, v56
	v_exp_f32_e32 v57, v57
	v_exp_f32_e32 v58, v58
	v_exp_f32_e32 v59, v59
	v_exp_f32_e32 v60, v60
	v_exp_f32_e32 v61, v61
	v_exp_f32_e32 v62, v62
	v_exp_f32_e32 v63, v63
	v_exp_f32_e32 v64, v64
	v_exp_f32_e32 v65, v65
	v_exp_f32_e32 v66, v66
	v_exp_f32_e32 v67, v67
	v_exp_f32_e32 v68, v68
	v_exp_f32_e32 v69, v69
	v_exp_f32_e32 v70, v70
	v_exp_f32_e32 v71, v71
	v_exp_f32_e32 v72, v72
	v_exp_f32_e32 v73, v73
	v_exp_f32_e32 v74, v74
	v_exp_f32_e32 v75, v75
	v_exp_f32_e32 v76, v76
	v_exp_f32_e32 v77, v77
	v_exp_f32_e32 v78, v78
	v_exp_f32_e32 v79, v79
	v_exp_f32_e32 v80, v80
	v_exp_f32_e32 v81, v81
	v_exp_f32_e32 v82, v82
	v_exp_f32_e32 v83, v83
	s_nop 0
	v_add_f32_e32 v218, v52, v53
	v_add_f32_e32 v219, v54, v55
	v_add_f32_e32 v218, v218, v56
	v_add_f32_e32 v219, v219, v57
	v_add_f32_e32 v218, v218, v58
	v_add_f32_e32 v219, v219, v59
	v_add_f32_e32 v218, v218, v60
	v_add_f32_e32 v219, v219, v61
	v_add_f32_e32 v218, v218, v62
	v_add_f32_e32 v219, v219, v63
	v_add_f32_e32 v218, v218, v64
	v_add_f32_e32 v219, v219, v65
	v_add_f32_e32 v218, v218, v66
	v_add_f32_e32 v219, v219, v67
	v_add_f32_e32 v218, v218, v68
	v_add_f32_e32 v219, v219, v69
	v_add_f32_e32 v218, v218, v70
	v_add_f32_e32 v219, v219, v71
	v_add_f32_e32 v218, v218, v72
	v_add_f32_e32 v219, v219, v73
	v_add_f32_e32 v218, v218, v74
	v_add_f32_e32 v219, v219, v75
	v_add_f32_e32 v218, v218, v76
	v_add_f32_e32 v219, v219, v77
	v_add_f32_e32 v218, v218, v78
	v_add_f32_e32 v219, v219, v79
	v_add_f32_e32 v218, v218, v80
	v_add_f32_e32 v219, v219, v81
	v_add_f32_e32 v218, v218, v82
	v_add_f32_e32 v219, v219, v83
	v_add_f32_e32 v218, v218, v219
	v_add_f32_e32 v213, v213, v218
	v_cvt_pk_bf16_f32 v100, v52, v53
	v_cvt_pk_bf16_f32 v101, v54, v55
	v_cvt_pk_bf16_f32 v102, v56, v57
	v_cvt_pk_bf16_f32 v103, v58, v59
	v_cvt_pk_bf16_f32 v104, v60, v61
	v_cvt_pk_bf16_f32 v105, v62, v63
	v_cvt_pk_bf16_f32 v106, v64, v65
	v_cvt_pk_bf16_f32 v107, v66, v67
	v_cvt_pk_bf16_f32 v108, v68, v69
	v_cvt_pk_bf16_f32 v109, v70, v71
	v_cvt_pk_bf16_f32 v110, v72, v73
	v_cvt_pk_bf16_f32 v111, v74, v75
	v_cvt_pk_bf16_f32 v112, v76, v77
	v_cvt_pk_bf16_f32 v113, v78, v79
	v_cvt_pk_bf16_f32 v114, v80, v81
	v_cvt_pk_bf16_f32 v115, v82, v83
	v_add_u32_e32 v221, s31, v234
	ds_write_b128 v221, v[100:103] offset:0
	ds_write_b128 v221, v[104:107] offset:1024
	ds_write_b128 v221, v[108:111] offset:2048
	ds_write_b128 v221, v[112:115] offset:3072
	s_waitcnt lgkmcnt(4)
	v_mfma_f32_32x32x16_bf16 v[148:163], v[100:103], v[116:119], v[148:163]
	v_mfma_f32_32x32x16_bf16 v[164:179], v[100:103], v[132:135], v[164:179]
	v_mfma_f32_32x32x16_bf16 v[148:163], v[104:107], v[120:123], v[148:163]
	v_mfma_f32_32x32x16_bf16 v[164:179], v[104:107], v[136:139], v[164:179]
	v_mfma_f32_32x32x16_bf16 v[148:163], v[108:111], v[124:127], v[148:163]
	v_mfma_f32_32x32x16_bf16 v[164:179], v[108:111], v[140:143], v[164:179]
	v_mfma_f32_32x32x16_bf16 v[148:163], v[112:115], v[128:131], v[148:163]
	v_mfma_f32_32x32x16_bf16 v[164:179], v[112:115], v[144:147], v[164:179]
; #define SBAR() __builtin_amdgcn_sched_barrier(0)
; __device__ __forceinline__ void pv(f32x16*o,int vb,bf16x8 pa0,bf16x8 pa1,bf16x8 pa2,bf16x8 pa3){
;   #pragma unroll
;   for(int d0=0;d0<2;++d0){s16x4 lo[4],hi[4];
;     #pragma unroll
;     for(int ks=0;ks<4;++ks){
;       asm volatile("ds_read_b64_tr_b16 %0,%1 offset:%c2":"=&v"(lo[ks]):"v"(vb),"i"(d0*4096+ks*1024):"memory");
;       asm volatile("ds_read_b64_tr_b16 %0,%1 offset:%c2":"=&v"(hi[ks]):"v"(vb),"i"(d0*4096+ks*1024+512):"memory");}
;     asm volatile("s_waitcnt lgkmcnt(0)":::"memory");SBAR();
;     ...
;     o[d0]=__builtin_amdgcn_mfma_f32_32x32x16_bf16(pa0,PK(0),o[d0],0,0,0);
;     o[d0]=__builtin_amdgcn_mfma_f32_32x32x16_bf16(pa1,PK(1),o[d0],0,0,0);
;     o[d0]=__builtin_amdgcn_mfma_f32_32x32x16_bf16(pa2,PK(2),o[d0],0,0,0);
;     o[d0]=__builtin_amdgcn_mfma_f32_32x32x16_bf16(pa3,PK(3),o[d0],0,0,0);
;     ...
;   }
; }
.Lat_Aend:
	s_branch .Lat_dma
.Lat_B:
	s_cmp_eq_u32 s17, 0
	s_cbranch_scc1 .Lat_Bend
	s_cmp_le_u32 s17, s16
	s_cbranch_scc0 .Lat_Bend
	v_add_u32_e32 v221, s32, v234
	ds_read_b128 v[100:103], v221 offset:0
	ds_read_b128 v[104:107], v221 offset:1024
	ds_read_b128 v[108:111], v221 offset:2048
	ds_read_b128 v[112:115], v221 offset:3072
	v_add_u32_e32 v216, s29, v233
	ds_read_b64_tr_b16 v[116:117], v216 offset:0
	ds_read_b64_tr_b16 v[118:119], v216 offset:512
	ds_read_b64_tr_b16 v[120:121], v216 offset:1024
	ds_read_b64_tr_b16 v[122:123], v216 offset:1536
	ds_read_b64_tr_b16 v[124:125], v216 offset:2048
	ds_read_b64_tr_b16 v[126:127], v216 offset:2560
	ds_read_b64_tr_b16 v[128:129], v216 offset:3072
	ds_read_b64_tr_b16 v[130:131], v216 offset:3584
	ds_read_b64_tr_b16 v[132:133], v216 offset:4096
	ds_read_b64_tr_b16 v[134:135], v216 offset:4608
	ds_read_b64_tr_b16 v[136:137], v216 offset:5120
	ds_read_b64_tr_b16 v[138:139], v216 offset:5632
	ds_read_b64_tr_b16 v[140:141], v216 offset:6144
	ds_read_b64_tr_b16 v[142:143], v216 offset:6656
	ds_read_b64_tr_b16 v[144:145], v216 offset:7168
	ds_read_b64_tr_b16 v[146:147], v216 offset:7680
	s_lshr_b32 s41, s40, 5
	v_add_u32_e32 v221, s41, v235
	ds_read_b32 v220, v221 offset:256
	s_waitcnt lgkmcnt(0)
	v_readfirstlane_b32 s42, v220
	s_cmp_eq_u32 s42, 0
	s_cbranch_scc1 .Lat_Bnores
	v_add_u32_e32 v221, s40, v235
	v_add_u32_e32 v221, v221, v241
	ds_read_b128 v[20:23], v221 offset:0
	ds_read_b128 v[24:27], v221 offset:32
	ds_read_b128 v[28:31], v221 offset:64
	ds_read_b128 v[32:35], v221 offset:96
	s_waitcnt lgkmcnt(0)
	v_mul_f32_e32 v148, v148, v20
	v_mul_f32_e32 v149, v149, v21
	v_mul_f32_e32 v150, v150, v22
	v_mul_f32_e32 v151, v151, v23
	v_mul_f32_e32 v152, v152, v24
	v_mul_f32_e32 v153, v153, v25
	v_mul_f32_e32 v154, v154, v26
	v_mul_f32_e32 v155, v155, v27
	v_mul_f32_e32 v156, v156, v28
	v_mul_f32_e32 v157, v157, v29
	v_mul_f32_e32 v158, v158, v30
	v_mul_f32_e32 v159, v159, v31
	v_mul_f32_e32 v160, v160, v32
	v_mul_f32_e32 v161, v161, v33
	v_mul_f32_e32 v162, v162, v34
	v_mul_f32_e32 v163, v163, v35
	v_mul_f32_e32 v164, v164, v20
	v_mul_f32_e32 v165, v165, v21
	v_mul_f32_e32 v166, v166, v22
	v_mul_f32_e32 v167, v167, v23
	v_mul_f32_e32 v168, v168, v24
	v_mul_f32_e32 v169, v169, v25
	v_mul_f32_e32 v170, v170, v26
	v_mul_f32_e32 v171, v171, v27
	v_mul_f32_e32 v172, v172, v28
	v_mul_f32_e32 v173, v173, v29
	v_mul_f32_e32 v174, v174, v30
	v_mul_f32_e32 v175, v175, v31
	v_mul_f32_e32 v176, v176, v32
	v_mul_f32_e32 v177, v177, v33
	v_mul_f32_e32 v178, v178, v34
	v_mul_f32_e32 v179, v179, v35
.Lat_Bnores:
	v_mfma_f32_32x32x16_bf16 v[148:163], v[100:103], v[116:119], v[148:163]
	v_mfma_f32_32x32x16_bf16 v[164:179], v[100:103], v[132:135], v[164:179]
	v_mfma_f32_32x32x16_bf16 v[148:163], v[104:107], v[120:123], v[148:163]
	v_mfma_f32_32x32x16_bf16 v[164:179], v[104:107], v[136:139], v[164:179]
	v_mfma_f32_32x32x16_bf16 v[148:163], v[108:111], v[124:127], v[148:163]
	v_mfma_f32_32x32x16_bf16 v[164:179], v[108:111], v[140:143], v[164:179]
	v_mfma_f32_32x32x16_bf16 v[148:163], v[112:115], v[128:131], v[148:163]
	v_mfma_f32_32x32x16_bf16 v[164:179], v[112:115], v[144:147], v[164:179]
.Lat_Bend:
.Lat_dma:
	s_add_i32 s34, s17, 2
	s_cmp_lt_u32 s34, s15
	s_cbranch_scc0 .Lat_nodma
	s_lshl_b32 s37, s4, 10
	s_add_i32 s38, s37, s27
	s_mov_b32 m0, s38
	s_nop 0
	global_load_lds_dwordx4 v236, s[18:19]
	s_add_i32 s38, s37, s30
	s_mov_b32 m0, s38
	s_nop 0
	global_load_lds_dwordx4 v237, s[20:21]
	s_add_i32 m0, s38, 0x2000
	s_nop 0
	global_load_lds_dwordx4 v238, s[20:21]
	s_add_u32 s18, s18, 0x10000
	s_addc_u32 s19, s19, 0
	s_add_u32 s20, s20, 0x10000
	s_addc_u32 s21, s21, 0
	s_waitcnt vmcnt(3) lgkmcnt(0)
	s_branch .Lat_bar

; __device__ __forceinline__ int crow(int r,int hi){return (r&3)+8*(r>>2)+4*hi;}
;   #define RESC() do{ if(resc){ asm volatile("s_waitcnt lgkmcnt(0)":::"memory"); \
;       _Pragma("unroll") for(int d_=0;d_<2;++d_) _Pragma("unroll") for(int r=0;r<16;++r)o[d_][r]*=wsf[crow(r,hi)]; } }while(0)
;   #define ROT() do{sl_prev=sl_cur;sl_cur=sl_next;sl_next=(sl_next==(NSLOT-1)*SLOTB)?0:sl_next+SLOTB;}while(0)
;   #define ENDW(tt) do{ if((tt)+3<NT){WAIT_BAR(2);} else if((tt)+2<NT){WAIT_BAR(1);} else {WAIT_BAR(0);} }while(0)
; template<int THRL,bool PART> __device__ __forceinline__ int attn_unit(const bf16*Qb,const bf16*__restrict__ Kh,const bf16*__restrict__ Vh,bf16*Ob,const int NT,const int vlim_in,char*shm,const int s0,const bool primed,const bf16*nKh,const bf16*nVh,bf16*fuseM,const float lam){
;     ...
;   for(;t+1<NT;t+=2){
;     STEP(pB0,pB1,pA0,pA1,t,(t+3<NT),(t+1<NT),(t+1<NT));       ENDW(t);   RESC(); ROT();
;     STEP(pA0,pA1,pB0,pB1,t+1,(t+4<NT),(t+2<NT),(t+2<NT));     ENDW(t+1); RESC(); ROT();
;   }
;     ...
;   if(act){
;   {auto rr=__builtin_amdgcn_permlane32_swap(__float_as_uint(l_reg),__float_as_uint(l_reg),false,false);l_reg=__uint_as_float(rr[0])+__uint_as_float(rr[1]);}
;   if(hi==0)wsf[32+r32]=l_reg;asm volatile("s_waitcnt lgkmcnt(0)":::"memory");
;   float rli[16];
;   #pragma unroll
;   for(int r=0;r<16;++r)rli[r]=__builtin_amdgcn_rcpf(wsf[32+crow(r,hi)]);
.Lat_bar:
	s_barrier
	s_add_i32 s24, s24, 1
	s_cmp_eq_u32 s24, 3
	s_cselect_b32 s24, 0, s24
	s_add_i32 s25, s25, 1
	s_and_b32 s25, s25, 3
	s_add_i32 s17, s17, 1
	s_cmp_le_u32 s17, s15
	s_cbranch_scc1 .Lat_t
	s_cmp_lg_u32 s6, 0
	s_cbranch_scc1 .Lat_eB
	v_mov_b32_e32 v218, v213
	s_nop 1
	v_permlane32_swap_b32_e32 v213, v218
	v_add_f32_e32 v213, v213, v218
	v_rcp_f32_e32 v213, v213
	v_add_u32_e32 v221, v235, v240
	s_nop 0
	ds_write_b32 v221, v213 offset:384
.Lat_eB:
	s_waitcnt lgkmcnt(0)
	s_barrier
	v_add_u32_e32 v221, v235, v241
	ds_read_b128 v[20:23], v221 offset:384
	ds_read_b128 v[24:27], v221 offset:416
	ds_read_b128 v[28:31], v221 offset:448
	ds_read_b128 v[32:35], v221 offset:480
	s_waitcnt lgkmcnt(0)
	s_nop 7
	s_nop 3
	v_mul_f32_e32 v148, v148, v20
	v_mul_f32_e32 v149, v149, v21
	v_mul_f32_e32 v150, v150, v22
	v_mul_f32_e32 v151, v151, v23
	v_mul_f32_e32 v152, v152, v24
	v_mul_f32_e32 v153, v153, v25
	v_mul_f32_e32 v154, v154, v26
	v_mul_f32_e32 v155, v155, v27
	v_mul_f32_e32 v156, v156, v28
	v_mul_f32_e32 v157, v157, v29
	v_mul_f32_e32 v158, v158, v30
	v_mul_f32_e32 v159, v159, v31
	v_mul_f32_e32 v160, v160, v32
	v_mul_f32_e32 v161, v161, v33
	v_mul_f32_e32 v162, v162, v34
	v_mul_f32_e32 v163, v163, v35
	v_mul_f32_e32 v164, v164, v20
	v_mul_f32_e32 v165, v165, v21
	v_mul_f32_e32 v166, v166, v22
	v_mul_f32_e32 v167, v167, v23
	v_mul_f32_e32 v168, v168, v24
	v_mul_f32_e32 v169, v169, v25
	v_mul_f32_e32 v170, v170, v26
	v_mul_f32_e32 v171, v171, v27
	v_mul_f32_e32 v172, v172, v28
	v_mul_f32_e32 v173, v173, v29
	v_mul_f32_e32 v174, v174, v30
	v_mul_f32_e32 v175, v175, v31
	v_mul_f32_e32 v176, v176, v32
	v_mul_f32_e32 v177, v177, v33
	v_mul_f32_e32 v178, v178, v34
	v_mul_f32_e32 v179, v179, v35
	s_cmp_lg_u32 s14, 0
	s_cbranch_scc1 .Lat_comb
	v_mov_b32_e32 v180, v148
	v_mov_b32_e32 v181, v149
	v_mov_b32_e32 v182, v150
	v_mov_b32_e32 v183, v151
	v_mov_b32_e32 v184, v152
	v_mov_b32_e32 v185, v153
	v_mov_b32_e32 v186, v154
	v_mov_b32_e32 v187, v155
	v_mov_b32_e32 v188, v156
	v_mov_b32_e32 v189, v157
	v_mov_b32_e32 v190, v158
	v_mov_b32_e32 v191, v159
	v_mov_b32_e32 v192, v160
	v_mov_b32_e32 v193, v161
	v_mov_b32_e32 v194, v162
	v_mov_b32_e32 v195, v163
	v_mov_b32_e32 v196, v164
	v_mov_b32_e32 v197, v165
	v_mov_b32_e32 v198, v166
	v_mov_b32_e32 v199, v167
	v_mov_b32_e32 v200, v168
	v_mov_b32_e32 v201, v169
	v_mov_b32_e32 v202, v170
	v_mov_b32_e32 v203, v171
	v_mov_b32_e32 v204, v172
	v_mov_b32_e32 v205, v173
	v_mov_b32_e32 v206, v174
	v_mov_b32_e32 v207, v175
	v_mov_b32_e32 v208, v176
	v_mov_b32_e32 v209, v177
	v_mov_b32_e32 v210, v178
	v_mov_b32_e32 v211, v179
	s_branch .Lat_udone
; __device__ __forceinline__ unsigned cvtpk_s(float lo,float hi){f32x2_t v={lo,hi};bf16x2_t b=__builtin_convertvector(v,bf16x2_t);return __builtin_bit_cast(unsigned,b);}
; template<int THRL,bool PART> __device__ __forceinline__ int attn_unit(const bf16*Qb,const bf16*__restrict__ Kh,const bf16*__restrict__ Vh,bf16*Ob,const int NT,const int vlim_in,char*shm,const int s0,const bool primed,const bf16*nKh,const bf16*nVh,bf16*fuseM,const float lam){
;     ...
;     asm volatile("s_waitcnt vmcnt(0)":::"memory"); __builtin_amdgcn_fence(__ATOMIC_ACQUIRE,"agent");
;     bf16*Mw=fuseM+(long)(wid*QBLK)*OP;
;     #pragma unroll
;     for(int i=0;i<4;++i){const int row=i*8+(lane>>3),ch=lane&7; const u32x4 v=*(const u32x4*)(stg+row*64+ch*8);
;       const bf16*gp=Ow+(long)row*OP+ch*8; const u32x4 a=*(const u32x4*)(gp-192), c1=*(const u32x4*)(gp-128), b=*(const u32x4*)(gp-64);
;       float d0[8],d1[8],ss=0.f;
;       #pragma unroll
;       for(int q=0;q<4;++q){ d0[2*q]=__uint_as_float(a[q]<<16)-lam*__uint_as_float(b[q]<<16); d0[2*q+1]=__uint_as_float(a[q]&0xffff0000u)-lam*__uint_as_float(b[q]&0xffff0000u);
;         d1[2*q]=__uint_as_float(c1[q]<<16)-lam*__uint_as_float(v[q]<<16); d1[2*q+1]=__uint_as_float(c1[q]&0xffff0000u)-lam*__uint_as_float(v[q]&0xffff0000u);
;         ss+=d0[2*q]*d0[2*q]+d0[2*q+1]*d0[2*q+1]+d1[2*q]*d1[2*q]+d1[2*q+1]*d1[2*q+1]; }
;       ss+=__shfl_xor(ss,1); ss+=__shfl_xor(ss,2); ss+=__shfl_xor(ss,4);
;       const float rn=rsqrtf(ss*(1.0f/128.0f)+1e-6f)*0.8f;
;       u32x4 w0,w1;
;       #pragma unroll
;       for(int q=0;q<4;++q){ w0[q]=cvtpk_s(d0[2*q]*rn,d0[2*q+1]*rn); w1[q]=cvtpk_s(d1[2*q]*rn,d1[2*q+1]*rn); }
;       *(u32x4*)(Mw+(long)row*OP+ch*8)=w0; *(u32x4*)(Mw+(long)row*OP+64+ch*8)=w1; }
;     } }
;   }
;   asm volatile("s_waitcnt lgkmcnt(0)\n\ts_barrier":::"memory");
.Lat_comb:
	v_mov_b32_e32 v218, s7
	v_fma_f32 v180, -v218, v148, v180
	v_fma_f32 v181, -v218, v149, v181
	v_fma_f32 v182, -v218, v150, v182
	v_fma_f32 v183, -v218, v151, v183
	v_fma_f32 v184, -v218, v152, v184
	v_fma_f32 v185, -v218, v153, v185
	v_fma_f32 v186, -v218, v154, v186
	v_fma_f32 v187, -v218, v155, v187
	v_fma_f32 v188, -v218, v156, v188
	v_fma_f32 v189, -v218, v157, v189
	v_fma_f32 v190, -v218, v158, v190
	v_fma_f32 v191, -v218, v159, v191
	v_fma_f32 v192, -v218, v160, v192
	v_fma_f32 v193, -v218, v161, v193
	v_fma_f32 v194, -v218, v162, v194
	v_fma_f32 v195, -v218, v163, v195
	v_fma_f32 v196, -v218, v164, v196
	v_fma_f32 v197, -v218, v165, v197
	v_fma_f32 v198, -v218, v166, v198
	v_fma_f32 v199, -v218, v167, v199
	v_fma_f32 v200, -v218, v168, v200
	v_fma_f32 v201, -v218, v169, v201
	v_fma_f32 v202, -v218, v170, v202
	v_fma_f32 v203, -v218, v171, v203
	v_fma_f32 v204, -v218, v172, v204
	v_fma_f32 v205, -v218, v173, v205
	v_fma_f32 v206, -v218, v174, v206
	v_fma_f32 v207, -v218, v175, v207
	v_fma_f32 v208, -v218, v176, v208
	v_fma_f32 v209, -v218, v177, v209
	v_fma_f32 v210, -v218, v178, v210
	v_fma_f32 v211, -v218, v179, v211
	s_mul_i32 s34, s5, 0x4200
	s_lshl_b32 s35, s6, 8
	s_add_i32 s34, s34, s35
	v_mul_u32_u24_e32 v221, 0x840, v2
	v_add_u32_e32 v221, v221, v240
	v_add_u32_e32 v221, s34, v221
	ds_write_b32 v221, v180 offset:0
	ds_write_b32 v221, v181 offset:528
	ds_write_b32 v221, v182 offset:1056
	ds_write_b32 v221, v183 offset:1584
	ds_write_b32 v221, v184 offset:4224
	ds_write_b32 v221, v185 offset:4752
	ds_write_b32 v221, v186 offset:5280
	ds_write_b32 v221, v187 offset:5808
	ds_write_b32 v221, v188 offset:8448
	ds_write_b32 v221, v189 offset:8976
	ds_write_b32 v221, v190 offset:9504
	ds_write_b32 v221, v191 offset:10032
	ds_write_b32 v221, v192 offset:12672
	ds_write_b32 v221, v193 offset:13200
	ds_write_b32 v221, v194 offset:13728
	ds_write_b32 v221, v195 offset:14256
	ds_write_b32 v221, v196 offset:128
	ds_write_b32 v221, v197 offset:656
	ds_write_b32 v221, v198 offset:1184
	ds_write_b32 v221, v199 offset:1712
	ds_write_b32 v221, v200 offset:4352
	ds_write_b32 v221, v201 offset:4880
	ds_write_b32 v221, v202 offset:5408
	ds_write_b32 v221, v203 offset:5936
	ds_write_b32 v221, v204 offset:8576
	ds_write_b32 v221, v205 offset:9104
	ds_write_b32 v221, v206 offset:9632
	ds_write_b32 v221, v207 offset:10160
	ds_write_b32 v221, v208 offset:12800
	ds_write_b32 v221, v209 offset:13328
	ds_write_b32 v221, v210 offset:13856
	ds_write_b32 v221, v211 offset:14384
	s_waitcnt lgkmcnt(0)
	s_barrier
	v_lshrrev_b32_e32 v222, 2, v252
	v_and_b32_e32 v223, 3, v252
	v_mul_u32_u24_e32 v221, 0x210, v222
	v_lshl_add_u32 v221, v223, 7, v221
	ds_read_b128 v[52:55], v221 offset:0
	ds_read_b128 v[56:59], v221 offset:16
	ds_read_b128 v[60:63], v221 offset:32
	ds_read_b128 v[64:67], v221 offset:48
	ds_read_b128 v[68:71], v221 offset:64
	ds_read_b128 v[72:75], v221 offset:80
	ds_read_b128 v[76:79], v221 offset:96
	ds_read_b128 v[80:83], v221 offset:112
	s_waitcnt lgkmcnt(0)
	v_mul_f32_e32 v218, v52, v52
	v_fmac_f32_e32 v218, v53, v53
	v_fmac_f32_e32 v218, v54, v54
	v_fmac_f32_e32 v218, v55, v55
	v_fmac_f32_e32 v218, v56, v56
	v_fmac_f32_e32 v218, v57, v57
	v_fmac_f32_e32 v218, v58, v58
	v_fmac_f32_e32 v218, v59, v59
	v_fmac_f32_e32 v218, v60, v60
	v_fmac_f32_e32 v218, v61, v61
	v_fmac_f32_e32 v218, v62, v62
	v_fmac_f32_e32 v218, v63, v63
	v_fmac_f32_e32 v218, v64, v64
	v_fmac_f32_e32 v218, v65, v65
	v_fmac_f32_e32 v218, v66, v66
	v_fmac_f32_e32 v218, v67, v67
	v_fmac_f32_e32 v218, v68, v68
	v_fmac_f32_e32 v218, v69, v69
	v_fmac_f32_e32 v218, v70, v70
	v_fmac_f32_e32 v218, v71, v71
	v_fmac_f32_e32 v218, v72, v72
	v_fmac_f32_e32 v218, v73, v73
	v_fmac_f32_e32 v218, v74, v74
	v_fmac_f32_e32 v218, v75, v75
	v_fmac_f32_e32 v218, v76, v76
	v_fmac_f32_e32 v218, v77, v77
	v_fmac_f32_e32 v218, v78, v78
	v_fmac_f32_e32 v218, v79, v79
	v_fmac_f32_e32 v218, v80, v80
	v_fmac_f32_e32 v218, v81, v81
	v_fmac_f32_e32 v218, v82, v82
	v_fmac_f32_e32 v218, v83, v83
	s_nop 1
	v_add_f32_dpp v218, v218, v218 quad_perm:[1,0,3,2] row_mask:0xf bank_mask:0xf
	s_nop 1
	v_add_f32_dpp v218, v218, v218 quad_perm:[2,3,0,1] row_mask:0xf bank_mask:0xf
	v_mov_b32_e32 v219, 0x358637bd
	v_fmamk_f32 v218, v218, 0x3c000000, v219
	v_rsq_f32_e32 v218, v218
	s_nop 0
	v_mul_f32_e32 v218, 0x3f4ccccd, v218
	v_mul_f32_e32 v52, v52, v218
	v_mul_f32_e32 v53, v53, v218
	v_mul_f32_e32 v54, v54, v218
	v_mul_f32_e32 v55, v55, v218
	v_mul_f32_e32 v56, v56, v218
	v_mul_f32_e32 v57, v57, v218
	v_mul_f32_e32 v58, v58, v218
	v_mul_f32_e32 v59, v59, v218
	v_mul_f32_e32 v60, v60, v218
	v_mul_f32_e32 v61, v61, v218
	v_mul_f32_e32 v62, v62, v218
	v_mul_f32_e32 v63, v63, v218
	v_mul_f32_e32 v64, v64, v218
	v_mul_f32_e32 v65, v65, v218
	v_mul_f32_e32 v66, v66, v218
	v_mul_f32_e32 v67, v67, v218
	v_mul_f32_e32 v68, v68, v218
	v_mul_f32_e32 v69, v69, v218
	v_mul_f32_e32 v70, v70, v218
	v_mul_f32_e32 v71, v71, v218
	v_mul_f32_e32 v72, v72, v218
	v_mul_f32_e32 v73, v73, v218
	v_mul_f32_e32 v74, v74, v218
	v_mul_f32_e32 v75, v75, v218
	v_mul_f32_e32 v76, v76, v218
	v_mul_f32_e32 v77, v77, v218
	v_mul_f32_e32 v78, v78, v218
	v_mul_f32_e32 v79, v79, v218
	v_mul_f32_e32 v80, v80, v218
	v_mul_f32_e32 v81, v81, v218
	v_mul_f32_e32 v82, v82, v218
	v_mul_f32_e32 v83, v83, v218
	v_cvt_pk_bf16_f32 v100, v52, v53
	v_cvt_pk_bf16_f32 v101, v54, v55
	v_cvt_pk_bf16_f32 v102, v56, v57
	v_cvt_pk_bf16_f32 v103, v58, v59
	v_cvt_pk_bf16_f32 v104, v60, v61
	v_cvt_pk_bf16_f32 v105, v62, v63
	v_cvt_pk_bf16_f32 v106, v64, v65
	v_cvt_pk_bf16_f32 v107, v66, v67
	v_cvt_pk_bf16_f32 v108, v68, v69
	v_cvt_pk_bf16_f32 v109, v70, v71
	v_cvt_pk_bf16_f32 v110, v72, v73
	v_cvt_pk_bf16_f32 v111, v74, v75
	v_cvt_pk_bf16_f32 v112, v76, v77
	v_cvt_pk_bf16_f32 v113, v78, v79
	v_cvt_pk_bf16_f32 v114, v80, v81
	v_cvt_pk_bf16_f32 v115, v82, v83
	s_add_u32 s50, s66, 0x2e00400
	s_addc_u32 s51, s67, 0
	s_lshl_b32 s36, s9, 23
	s_add_u32 s50, s50, s36
	s_addc_u32 s51, s51, 0
	s_lshl_b32 s36, s13, 18
	s_add_u32 s50, s50, s36
	s_addc_u32 s51, s51, 0
	s_lshl_b32 s36, s10, 8
	s_add_u32 s50, s50, s36
	s_addc_u32 s51, s51, 0
	v_lshlrev_b32_e32 v221, 11, v222
	v_lshl_add_u32 v221, v223, 6, v221
	global_store_dwordx4 v221, v[100:103], s[50:51]
	global_store_dwordx4 v221, v[104:107], s[50:51] offset:16
	global_store_dwordx4 v221, v[108:111], s[50:51] offset:32
	global_store_dwordx4 v221, v[112:115], s[50:51] offset:48
.Lat_udone:
	s_barrier
	s_add_i32 s14, s14, 1
	s_cmp_lt_u32 s14, 2
	s_cbranch_scc1 .Lat_j
	s_add_i32 s12, s12, 1
	s_cmp_lt_u32 s12, 4
	s_cbranch_scc1 .Lat_blk
	s_add_i32 s8, s8, s69
	s_cmpk_gt_i32 s8, 0xff
	s_cbranch_scc0 .Lat_v
	s_branch .LBB0_1021

; #define LAS __attribute__((address_space(3)))
; template <int NMT> __device__ __forceinline__ void ssd_out_item(const int ci, const int mt0, const float* DT, const bf16* XT, const bf16* BN, const bf16* CN, const bf16* HST, const bf16* Z, const float* ssd_norm, ...
;     ...
;         for (int ks = 0; ks < 2; ++ks) {
;             bf16x8 xf[4];
; #pragma unroll
;             for (int nt = 0; nt < 4; ++nt) xf[nt] = *(const bf16x8*)(XT + ((size_t)(ci * 8 + h) * 64 + 16 * nt + fr) * 64 + 32 * ks + 8 * fq);
;             const int s0 = 32 * ks + 8 * fq;
;             const f32x4 as0 = *(const LAS f32x4*)(sAcs + h * 64 + s0), as1 = *(const LAS f32x4*)(sAcs + h * 64 + s0 + 4), d0 = *(const LAS f32x4*)(sDt + h * 64 + s0), d1 = *(const LAS f32x4*)(sDt + h * 64 + s0 + 4);
; #pragma unroll
;             for (int mt = 0; mt < NMT; ++mt) { const int l = 16 * (mt0 + mt) + fr; const float al = sAcs[h * 64 + l];
;                 const f32x4 c0 = *(const LAS f32x4*)(sCB + (g * 64 + l) * 68 + s0), c1 = *(const LAS f32x4*)(sCB + (g * 64 + l) * 68 + s0 + 4);
;                 float mv[8];
; #pragma unroll
;                 for (int j = 0; j < 4; ++j) { mv[j] = (s0 + j <= l) ? c0[j] * __expf(fminf(al - as0[j], 0.f)) * d0[j] : 0.f; mv[4 + j] = (s0 + 4 + j <= l) ? c1[j] * __expf(fminf(al - as1[j], 0.f)) * d1[j] : 0.f; }
; #pragma unroll
;                 for (int j = 0; j < 8; ++j) if (s0 + j == l) mv[j] += Dh;
; __device__ __forceinline__ void ph_ssd_out(const float* DT, const bf16* XT, const bf16* BN, const bf16* CN, const bf16* HST, const bf16* Z, const float* a_log, const float* d_skip, const float* ssd_norm, ...
;     asm volatile("" : "+v"(tid)); const int lane = tid & 63, wave = __builtin_amdgcn_readfirstlane(tid >> 6);
;     const float A = -__expf(a_log[wave]), Dh = d_skip[wave];
;     for (int ci = vcu; ci < 512; ci += G) ssd_out_item<4>(ci, 0, DT, XT, BN, CN, HST, Z, ssd_norm, MIXA, lds, A, Dh, lane, wave);
.LBB0_1155:
	v_readlane_b32 s4, v254, 0
	s_cmp_lt_i32 s4, 9
	v_readlane_b32 s5, v254, 1
	s_cselect_b64 s[2:3], -1, 0
	s_and_b64 s[4:5], s[2:3], s[0:1]
	s_andn2_b64 vcc, exec, s[4:5]
	v_readlane_b32 s6, v254, 2
	v_readlane_b32 s7, v254, 3
	s_cbranch_vccnz .LBB0_1186
	v_writelane_b32 v254, s4, 39
	s_waitcnt lgkmcnt(0)
	s_add_u32 s0, s66, 0x16400000
	s_addc_u32 s1, s67, 0
	v_writelane_b32 v254, s5, 40
	v_writelane_b32 v254, s0, 47
	v_mov_b32_e32 v2, v252
	s_nop 0
	v_writelane_b32 v254, s1, 48
	s_add_u32 s0, s66, 0x18500000
	v_writelane_b32 v254, s0, 24
	s_addc_u32 s0, s67, 0
	v_writelane_b32 v254, s0, 26
	s_add_u32 s0, s66, 0x19600000
	v_writelane_b32 v254, s0, 28
	s_addc_u32 s0, s67, 0
	v_writelane_b32 v254, s0, 30
	s_add_u32 s0, s66, 0x1b800000
	s_addc_u32 s1, s67, 0
	v_writelane_b32 v254, s0, 37
	s_nop 1
	v_writelane_b32 v254, s1, 38
	s_add_u32 s0, s66, 0xb000000
	v_writelane_b32 v254, s0, 18
	s_addc_u32 s0, s67, 0
	v_writelane_b32 v254, s0, 23
	s_add_u32 s0, s66, 0x2e00000
	v_writelane_b32 v254, s0, 16
	s_addc_u32 s0, s67, 0
	v_writelane_b32 v254, s0, 17
	s_load_dwordx2 s[0:1], s[58:59], 0x90
	s_waitcnt lgkmcnt(0)
	s_load_dwordx2 s[2:3], s[58:59], 0x98
	s_waitcnt lgkmcnt(0)
	s_load_dwordx2 s[4:5], s[58:59], 0xa0
	s_waitcnt lgkmcnt(0)
	s_nop 0
	v_writelane_b32 v254, s4, 21
	v_and_b32_e32 v110, 63, v2
	v_and_b32_e32 v80, 15, v2
	v_writelane_b32 v254, s5, 22
	v_readfirstlane_b32 s4, v2
	s_ashr_i32 s58, s4, 6
	s_ashr_i32 s59, s58, 31
	s_lshl_b64 s[8:9], s[58:59], 2
	s_add_u32 s0, s0, s8
	s_addc_u32 s1, s1, s9
	v_mov_b64_e32 v[0:1], s[0:1]
	flat_load_dword v3, v[0:1]
	s_add_u32 s0, s2, s8
	s_addc_u32 s1, s3, s9
	v_mov_b64_e32 v[0:1], s[0:1]
	flat_load_dword v81, v[0:1]
	s_add_u32 s0, s66, s8
	s_addc_u32 s1, s67, s9
	s_add_u32 s64, s0, 0x200000
	s_addc_u32 s65, s1, 0
	v_writelane_b32 v254, s4, 32
	v_lshrrev_b32_e32 v112, 4, v110
	v_cmp_eq_u32_e64 s[14:15], 0, v110
	v_cmp_gt_u32_e64 s[2:3], 2, v110
	v_cmp_gt_u32_e64 s[4:5], 4, v110
	v_cmp_gt_u32_e64 s[6:7], 8, v110
	s_cmpk_gt_i32 s92, 0x1ff
	v_cmp_gt_u32_e64 s[8:9], 16, v110
	v_cmp_gt_u32_e64 s[10:11], 32, v110
	v_and_b32_e32 v82, 48, v110
	v_and_b32_e32 v113, 48, v2
	s_waitcnt vmcnt(0) lgkmcnt(0)
	v_mul_f32_e32 v0, 0x3fb8aa3b, v3
	v_exp_f32_e32 v111, v0
	s_cbranch_scc1 .LBB0_1167
	v_readlane_b32 s0, v254, 32
	s_ashr_i32 s1, s0, 8
	s_lshl_b32 s12, s58, 4
	s_and_b32 s16, s12, 48
	s_lshl_b32 s12, s1, 7
	s_ashr_i32 s13, s12, 31
	s_andn2_b32 s0, s0, 63
	s_lshl_b64 s[12:13], s[12:13], 1
	v_readlane_b32 s17, v254, 28
	s_add_u32 s18, s17, s12
	v_readlane_b32 s17, v254, 30
	v_mov_b32_e32 v85, 0
	s_addc_u32 s19, s17, s13
	v_lshlrev_b32_e32 v84, 3, v112
	v_mov_b32_e32 v83, v85
	v_lshl_add_u64 v[86:87], s[18:19], 0, v[82:83]
	v_cmp_lt_u32_e64 s[18:19], v84, v80
	v_or_b32_e32 v6, 5, v84
	v_or_b32_e32 v7, 4, v84
	v_writelane_b32 v253, s18, 29
	v_or_b32_e32 v10, 3, v84
	v_or_b32_e32 v11, 2, v84
	v_writelane_b32 v253, s19, 30
	v_cmp_gt_u32_e64 s[18:19], v6, v80
	v_mbcnt_lo_u32_b32 v0, -1, 0
	v_or_b32_e32 v8, 7, v84
	v_writelane_b32 v253, s18, 27
	v_mbcnt_hi_u32_b32 v0, -1, v0
	v_and_b32_e32 v1, 64, v0
	v_writelane_b32 v253, s19, 28
	v_cmp_gt_u32_e64 s[18:19], v7, v80
	v_add_u32_e32 v2, -1, v0
	v_or_b32_e32 v9, 6, v84
	v_writelane_b32 v253, s18, 25
	v_cmp_lt_i32_e32 vcc, v2, v1
	v_or_b32_e32 v5, 1, v84
	v_writelane_b32 v253, s19, 26
	v_cmp_gt_u32_e64 s[18:19], v10, v80
	v_cndmask_b32_e32 v2, v2, v0, vcc
	v_lshlrev_b32_e32 v114, 2, v2
	v_writelane_b32 v253, s18, 23
	v_add_u32_e32 v2, -2, v0
	v_cmp_lt_i32_e32 vcc, v2, v1
	v_writelane_b32 v253, s19, 24
	v_cmp_gt_u32_e64 s[18:19], v11, v80
	v_cndmask_b32_e32 v2, v2, v0, vcc
	v_lshlrev_b32_e32 v115, 2, v2
	v_writelane_b32 v253, s18, 21
	v_add_u32_e32 v2, -4, v0
	v_cmp_lt_i32_e32 vcc, v2, v1
	v_writelane_b32 v253, s19, 22
	v_cmp_gt_u32_e64 s[18:19], v8, v80
	v_cndmask_b32_e32 v2, v2, v0, vcc
	v_lshlrev_b32_e32 v116, 2, v2
	v_writelane_b32 v253, s18, 19
	v_add_u32_e32 v2, -8, v0
	v_cmp_lt_i32_e32 vcc, v2, v1
	v_writelane_b32 v253, s19, 20
	v_cmp_gt_u32_e64 s[18:19], v9, v80
	v_cndmask_b32_e32 v2, v2, v0, vcc
	v_lshlrev_b32_e32 v117, 2, v2
	v_writelane_b32 v253, s18, 17
	v_add_u32_e32 v2, -16, v0
	v_cmp_lt_i32_e32 vcc, v2, v1
	v_writelane_b32 v253, s19, 18
	v_cmp_eq_u32_e64 s[18:19], v5, v80
	v_cndmask_b32_e32 v2, v2, v0, vcc
	v_lshlrev_b32_e32 v118, 2, v2
	v_writelane_b32 v253, s18, 15
	v_subrev_u32_e32 v2, 32, v0
	v_readlane_b32 s17, v254, 24
	v_writelane_b32 v253, s19, 16
	v_cmp_eq_u32_e64 s[18:19], v11, v80
	v_cmp_lt_i32_e32 vcc, v2, v1
	s_add_u32 s12, s17, s12
	v_writelane_b32 v253, s18, 13
	v_readlane_b32 s17, v254, 26
	v_or_b32_e32 v12, 16, v80
	v_writelane_b32 v253, s19, 14
	v_cmp_eq_u32_e64 s[18:19], v10, v80
	v_cndmask_b32_e32 v2, v2, v0, vcc
	s_addc_u32 s13, s17, s13
	v_writelane_b32 v253, s18, 11
	s_lshl_b32 s1, s1, 6
	v_lshlrev_b32_e32 v119, 2, v2
	v_writelane_b32 v253, s19, 12
	v_cmp_eq_u32_e64 s[18:19], v7, v80
	v_or_b32_e32 v2, s0, v110
	v_lshl_add_u64 v[88:89], s[12:13], 0, v[82:83]
	v_writelane_b32 v253, s18, 9
	s_or_b32 s12, s1, s16
	v_lshl_add_u32 v120, v2, 2, 0
	v_writelane_b32 v253, s19, 10
	v_cmp_eq_u32_e64 s[18:19], v6, v80
	v_or_b32_e32 v2, s12, v80
	v_readlane_b32 s12, v254, 47
	v_writelane_b32 v253, s18, 7
	v_readlane_b32 s13, v254, 48
	v_or_b32_e32 v125, 48, v110
	v_writelane_b32 v253, s19, 8
	v_cmp_eq_u32_e64 s[18:19], v9, v80
	s_movk_i32 s17, 0x110
	v_lshl_add_u64 v[90:91], s[12:13], 0, v[82:83]
	v_writelane_b32 v253, s18, 5
	s_lshl_b32 s12, s0, 2
	v_or_b32_e32 v4, s1, v80
	v_writelane_b32 v253, s19, 6
	v_cmp_eq_u32_e64 s[18:19], v8, v80
	v_or_b32_e32 v13, s1, v12
	v_cmp_eq_u32_e64 s[70:71], v7, v12
	v_writelane_b32 v253, s18, 3
; #define LAS __attribute__((address_space(3)))
; __device__ __forceinline__ unsigned pk2(float lo, float hi) { return pg8::cvt_pk_bf16(lo, hi); }
; template <int NMT> __device__ __forceinline__ void ssd_out_item(const int ci, const int mt0, const float* DT, const bf16* XT, const bf16* BN, const bf16* CN, const bf16* HST, const bf16* Z, const float* ssd_norm, ...
;     ...
;             for (int nt = 0; nt < 4; ++nt) { const f32x4 nw = *(const f32x4*)(ssd_norm + h * 64 + 16 * nt + 4 * fq); const f32x4 o = acc[nt][mt] * rstd * nw;
;                 v2u ow; ow.x = pk2(o[0], o[1]); ow.y = pk2(o[2], o[3]); *(v2u*)(MIXA + (size_t)(row0 + l) * 1024 + h * 64 + 16 * nt + 4 * fq) = ow; } }
; __device__ __forceinline__ void ph_ssd_out(const float* DT, const bf16* XT, const bf16* BN, const bf16* CN, const bf16* HST, const bf16* Z, const float* a_log, const float* d_skip, const float* ssd_norm, ...
;     asm volatile("" : "+v"(tid)); const int lane = tid & 63, wave = __builtin_amdgcn_readfirstlane(tid >> 6);
;     const float A = -__expf(a_log[wave]), Dh = d_skip[wave];
;     for (int ci = vcu; ci < 512; ci += G) ssd_out_item<4>(ci, 0, DT, XT, BN, CN, HST, Z, ssd_norm, MIXA, lds, A, Dh, lane, wave);
	v_cmp_eq_u32_e64 s[72:73], v6, v12
	v_mul_lo_u32 v2, v2, s17
	v_writelane_b32 v253, s19, 4
	v_cmp_gt_u32_e64 s[18:19], v84, v12
	s_add_i32 s22, s12, 0
	v_mul_lo_u32 v4, v4, s17
	v_writelane_b32 v253, s18, 1
	v_mul_lo_u32 v13, v13, s17
	v_xor_b32_e32 v16, 16, v0
	v_writelane_b32 v253, s19, 2
	v_cmp_lt_u32_e64 s[18:19], v84, v12
	v_add_u32_e32 v1, 64, v1
	v_cmp_eq_u32_e64 s[76:77], v8, v12
	v_writelane_b32 v254, s18, 63
	v_cmp_lt_i32_e32 vcc, v16, v1
	v_xor_b32_e32 v17, 32, v0
	v_writelane_b32 v253, s19, 0
	v_cmp_gt_u32_e64 s[18:19], v6, v12
	v_lshlrev_b32_e32 v3, 5, v112
	v_cmp_eq_u32_e64 s[74:75], v9, v12
	v_writelane_b32 v254, s18, 61
	v_cndmask_b32_e32 v16, v0, v16, vcc
	v_cmp_lt_i32_e32 vcc, v17, v1
	v_writelane_b32 v254, s19, 62
	v_cmp_gt_u32_e64 s[18:19], v7, v12
	v_or_b32_e32 v7, s1, v125
	v_mul_lo_u32 v127, v7, s17
	v_writelane_b32 v254, s18, 59
	v_add_u32_e32 v2, 0, v2
	v_add_u32_e32 v121, s22, v3
	v_writelane_b32 v254, s19, 60
	v_cmp_gt_u32_e64 s[18:19], v10, v12
	v_add_u32_e32 v122, 0, v3
	v_lshlrev_b32_e32 v3, 2, v80
	v_writelane_b32 v254, s18, 57
	v_or_b32_e32 v7, 33, v84
	v_or_b32_e32 v14, 35, v84
	v_writelane_b32 v254, s19, 58
	v_cmp_gt_u32_e64 s[18:19], v11, v12
	v_or_b32_e32 v15, 34, v84
	v_cndmask_b32_e32 v0, v0, v17, vcc
	v_writelane_b32 v254, s18, 55
	v_add_u32_e32 v123, s22, v3
	v_cmp_gt_u32_e64 s[12:13], v84, v80
	v_writelane_b32 v254, s19, 56
	v_cmp_gt_u32_e64 s[18:19], v8, v12
	v_or_b32_e32 v8, 32, v84
	v_cmp_eq_u32_e64 s[28:29], v84, v80
	v_writelane_b32 v254, s18, 53
	v_lshlrev_b32_e32 v130, 2, v16
	v_lshlrev_b32_e32 v131, 2, v0
	v_writelane_b32 v254, s19, 54
	v_cmp_gt_u32_e64 s[18:19], v9, v12
	v_lshlrev_b32_e32 v9, 2, v8
	v_add_u32_e32 v128, s22, v9
	v_writelane_b32 v254, s18, 51
	v_add_u32_e32 v129, 0, v9
	v_or_b32_e32 v9, 37, v84
	v_writelane_b32 v254, s19, 52
	v_cmp_eq_u32_e64 s[18:19], v84, v12
	v_lshl_add_u32 v132, v110, 2, s22
	v_or_b32_e32 v133, s16, v80
	v_writelane_b32 v254, s18, 45
	v_add_u32_e32 v134, v2, v113
	v_add_u32_e32 v135, v122, v4
	v_writelane_b32 v254, s19, 46
	v_cmp_eq_u32_e64 s[18:19], v5, v12
	v_or_b32_e32 v5, 32, v80
	v_or_b32_e32 v6, s1, v5
	v_writelane_b32 v254, s18, 43
	s_ashr_i32 s1, s0, 31
	v_mul_lo_u32 v124, v6, s17
	v_writelane_b32 v254, s19, 44
	v_cmp_eq_u32_e64 s[18:19], v11, v12
	v_lshlrev_b32_e32 v6, 2, v125
	v_or_b32_e32 v11, 39, v84
	v_writelane_b32 v254, s18, 49
	v_add_u32_e32 v126, s22, v6
	v_cmp_gt_u32_e64 s[78:79], v7, v5
	v_writelane_b32 v254, s19, 50
	v_cmp_eq_u32_e64 s[18:19], v10, v12
	v_or_b32_e32 v10, 36, v84
	v_or_b32_e32 v12, 38, v84
	v_writelane_b32 v254, s18, 41
	v_cmp_gt_u32_e64 s[80:81], v9, v5
	v_cmp_gt_u32_e64 s[82:83], v10, v5
	v_writelane_b32 v254, s19, 42
	s_lshl_b64 s[18:19], s[0:1], 1
	v_readlane_b32 s17, v254, 18
	s_add_u32 s20, s17, s18
	v_readlane_b32 s17, v254, 23
	s_addc_u32 s21, s17, s19
	v_lshl_add_u64 v[92:93], s[20:21], 0, v[84:85]
	s_lshl_b64 s[0:1], s[0:1], 2
	v_readlane_b32 s20, v254, 21
	v_readlane_b32 s21, v254, 22
	s_add_u32 s0, s20, s0
	s_addc_u32 s1, s21, s1
	v_lshl_add_u64 v[96:97], s[0:1], 0, v[82:83]
	v_readlane_b32 s0, v254, 16
	s_add_u32 s0, s0, s18
	v_readlane_b32 s1, v254, 17
	v_readlane_b32 s20, v254, 37
	s_addc_u32 s1, s1, s19
	v_readlane_b32 s68, v254, 13
	v_readlane_b32 s21, v254, 38
	v_lshl_add_u64 v[98:99], s[0:1], 0, v[84:85]
	s_lshl_b32 s0, s68, 3
	v_lshl_add_u64 v[94:95], s[20:21], 0, v[82:83]
	v_add_u32_e32 v83, 0, v3
	v_add_u32_e32 v84, 0, v6
	s_add_i32 s66, s58, s0
	s_lshl_b32 s59, s69, 3
	s_lshl_b32 s33, s68, 6
	s_lshl_b32 s63, s69, 6
	v_add_u32_e32 v136, v122, v13
	v_mov_b32_e32 v137, 0x358637bd
	s_mov_b32 s62, 0x800000
	v_mov_b32_e32 v138, v110
	v_mov_b32_e32 v139, v80
	v_cmp_gt_u32_e64 s[84:85], v14, v5
	v_cmp_gt_u32_e64 s[86:87], v15, v5
	v_cmp_gt_u32_e64 s[88:89], v11, v5
	v_cmp_gt_u32_e64 s[90:91], v12, v5
	v_cmp_eq_u32_e64 s[92:93], v7, v5
	v_cmp_eq_u32_e64 s[94:95], v15, v5
	v_cmp_eq_u32_e64 s[96:97], v14, v5
	v_cmp_eq_u32_e64 s[0:1], v10, v5
	v_cmp_eq_u32_e64 s[16:17], v9, v5
	v_cmp_eq_u32_e64 s[18:19], v12, v5
	v_cmp_eq_u32_e64 s[20:21], v11, v5
	v_cmp_gt_u32_e64 s[22:23], v7, v125
	v_cmp_gt_u32_e64 s[24:25], v8, v125
	v_cmp_gt_u32_e64 s[26:27], v9, v125
	v_cmp_gt_u32_e64 s[30:31], v10, v125
	v_cmp_gt_u32_e64 s[34:35], v14, v125
	v_cmp_gt_u32_e64 s[36:37], v15, v125
	v_cmp_gt_u32_e64 s[38:39], v11, v125
	v_cmp_gt_u32_e64 s[40:41], v12, v125
	v_cmp_eq_u32_e64 s[42:43], v8, v125
	v_cmp_eq_u32_e64 s[44:45], v7, v125
	v_cmp_eq_u32_e64 s[46:47], v15, v125
	v_cmp_eq_u32_e64 s[48:49], v14, v125
	v_cmp_eq_u32_e64 s[50:51], v10, v125
	v_cmp_eq_u32_e64 s[52:53], v9, v125
	v_cmp_eq_u32_e64 s[54:55], v12, v125
	v_cmp_eq_u32_e64 s[56:57], v11, v125
	global_load_dwordx4 v[204:207], v[96:97], off
	global_load_dwordx4 v[208:211], v[96:97], off offset:64
	global_load_dwordx4 v[212:215], v[96:97], off offset:128
	global_load_dwordx4 v[216:219], v[96:97], off offset:192
	s_waitcnt vmcnt(0)
	s_branch .LBB0_1159
; __device__ __forceinline__ unsigned pk2(float lo, float hi) { return pg8::cvt_pk_bf16(lo, hi); }
; template <int NMT> __device__ __forceinline__ void ssd_out_item(const int ci, const int mt0, const float* DT, const bf16* XT, const bf16* BN, const bf16* CN, const bf16* HST, const bf16* Z, const float* ssd_norm, ...
;     ...
;         for (int mt = 0; mt < NMT; ++mt) { const int l = 16 * (mt0 + mt) + fr; float tot = 0.f;
; #pragma unroll
;             for (int w = 0; w < 8; ++w) tot += sSS[w * 64 + l];
;             const float rstd = rsqrtf(tot * (1.0f / 512.0f) + EPSN);
; #pragma unroll
;             for (int nt = 0; nt < 4; ++nt) { const f32x4 nw = *(const f32x4*)(ssd_norm + h * 64 + 16 * nt + 4 * fq); const f32x4 o = acc[nt][mt] * rstd * nw;
;                 v2u ow; ow.x = pk2(o[0], o[1]); ow.y = pk2(o[2], o[3]); *(v2u*)(MIXA + (size_t)(row0 + l) * 1024 + h * 64 + 16 * nt + 4 * fq) = ow; } }
.LBB0_1158:
	s_or_b64 exec, exec, s[60:61]
	s_waitcnt lgkmcnt(0)
	s_barrier
	ds_read2st64_b32 v[48:49], v83 offset0:152 offset1:153
	s_add_i32 s68, s68, s69
	s_add_i32 s66, s66, s59
	v_add_u32_e32 v125, s63, v125
	v_add_u32_e32 v139, s63, v139
	s_waitcnt lgkmcnt(0)
	v_add_f32_e32 v48, 0, v48
	v_add_f32_e32 v50, v48, v49
	ds_read2st64_b32 v[48:49], v83 offset0:154 offset1:155
	v_add_u32_e32 v133, s63, v133
	v_add_u32_e32 v138, s63, v138
	s_cmpk_gt_i32 s68, 0x1ff
	s_waitcnt lgkmcnt(0)
	v_add_f32_e32 v48, v50, v48
	v_add_f32_e32 v50, v48, v49
	ds_read2st64_b32 v[48:49], v83 offset0:156 offset1:157
	s_waitcnt lgkmcnt(0)
	v_add_f32_e32 v48, v50, v48
	v_add_f32_e32 v50, v48, v49
	ds_read2st64_b32 v[48:49], v83 offset0:158 offset1:159
	s_waitcnt lgkmcnt(0)
	v_add_f32_e32 v48, v50, v48
	v_add_f32_e32 v48, v48, v49
	v_fmamk_f32 v48, v48, 0x3b000000, v137
	v_cmp_gt_f32_e32 vcc, s62, v48
	v_mul_f32_e32 v49, 0x4b800000, v48
	s_nop 0
	v_cndmask_b32_e32 v48, v48, v49, vcc
	v_rsq_f32_e32 v48, v48
	s_nop 0
	v_mul_f32_e32 v49, 0x45800000, v48
	v_cndmask_b32_e32 v60, v48, v49, vcc
	v_lshlrev_b64 v[48:49], 11, v[104:105]
	v_lshl_add_u64 v[62:63], v[98:99], 0, v[48:49]
	v_mov_b64_e32 v[48:49], v[204:205]
	v_mov_b64_e32 v[50:51], v[206:207]
	v_pk_mul_f32 v[64:65], v[72:73], v[60:61] op_sel_hi:[1,0]
	v_pk_mul_f32 v[66:67], v[74:75], v[60:61] op_sel_hi:[1,0]
	v_pk_mul_f32 v[56:57], v[56:57], v[60:61] op_sel_hi:[1,0]
	v_pk_mul_f32 v[58:59], v[58:59], v[60:61] op_sel_hi:[1,0]
	v_pk_mul_f32 v[52:53], v[52:53], v[60:61] op_sel_hi:[1,0]
	v_pk_mul_f32 v[54:55], v[54:55], v[60:61] op_sel_hi:[1,0]
	s_waitcnt lgkmcnt(0)
	v_pk_mul_f32 v[48:49], v[48:49], v[64:65]
	v_pk_mul_f32 v[50:51], v[50:51], v[66:67]
	v_cvt_pk_bf16_f32 v48, v48, v49
	v_pk_mul_f32 v[64:65], v[68:69], v[60:61] op_sel_hi:[1,0]
	v_cvt_pk_bf16_f32 v49, v50, v51
	global_store_dwordx2 v[62:63], v[48:49], off
	v_mov_b64_e32 v[48:49], v[208:209]
	v_mov_b64_e32 v[50:51], v[210:211]
	v_pk_mul_f32 v[66:67], v[70:71], v[60:61] op_sel_hi:[1,0]
	s_waitcnt lgkmcnt(0)
	v_pk_mul_f32 v[48:49], v[48:49], v[64:65]
	v_pk_mul_f32 v[50:51], v[50:51], v[66:67]
	v_cvt_pk_bf16_f32 v48, v48, v49
	s_nop 0
	v_cvt_pk_bf16_f32 v49, v50, v51
	global_store_dwordx2 v[62:63], v[48:49], off offset:32
	v_mov_b64_e32 v[48:49], v[212:213]
	v_mov_b64_e32 v[50:51], v[214:215]
	s_waitcnt lgkmcnt(0)
	v_pk_mul_f32 v[48:49], v[48:49], v[56:57]
	v_pk_mul_f32 v[50:51], v[50:51], v[58:59]
	v_cvt_pk_bf16_f32 v48, v48, v49
	s_nop 0
	v_cvt_pk_bf16_f32 v49, v50, v51
	global_store_dwordx2 v[62:63], v[48:49], off offset:64
	v_mov_b64_e32 v[48:49], v[216:217]
	v_mov_b64_e32 v[50:51], v[218:219]
	s_waitcnt lgkmcnt(0)
	v_pk_mul_f32 v[50:51], v[54:55], v[50:51]
	v_pk_mul_f32 v[48:49], v[52:53], v[48:49]
	s_nop 0
	v_cvt_pk_bf16_f32 v48, v48, v49
	v_cvt_pk_bf16_f32 v49, v50, v51
	v_add_u32_e32 v50, 64, v83
	global_store_dwordx2 v[62:63], v[48:49], off offset:96
	ds_read2st64_b32 v[48:49], v50 offset0:152 offset1:153
	s_waitcnt lgkmcnt(0)
	v_add_f32_e32 v48, 0, v48
	v_add_f32_e32 v51, v48, v49
	ds_read2st64_b32 v[48:49], v50 offset0:154 offset1:155
	s_waitcnt lgkmcnt(0)
	v_add_f32_e32 v48, v51, v48
	v_add_f32_e32 v51, v48, v49
	ds_read2st64_b32 v[48:49], v50 offset0:156 offset1:157
	s_waitcnt lgkmcnt(0)
	v_add_f32_e32 v48, v51, v48
	v_add_f32_e32 v51, v48, v49
	ds_read2st64_b32 v[48:49], v50 offset0:158 offset1:159
	s_waitcnt lgkmcnt(0)
	v_add_f32_e32 v48, v51, v48
	v_add_f32_e32 v48, v48, v49
	v_fmamk_f32 v48, v48, 0x3b000000, v137
	v_cmp_gt_f32_e32 vcc, s62, v48
	v_mul_f32_e32 v49, 0x4b800000, v48
	s_nop 0
	v_cndmask_b32_e32 v48, v48, v49, vcc
	v_rsq_f32_e32 v48, v48
	s_nop 0
	v_mul_f32_e32 v49, 0x45800000, v48
	v_cndmask_b32_e32 v52, v48, v49, vcc
	v_lshlrev_b64 v[48:49], 11, v[102:103]
	v_lshl_add_u64 v[54:55], v[98:99], 0, v[48:49]
	v_mov_b64_e32 v[48:49], v[204:205]
	v_mov_b64_e32 v[50:51], v[206:207]
	v_pk_mul_f32 v[44:45], v[44:45], v[52:53] op_sel_hi:[1,0]
	v_pk_mul_f32 v[46:47], v[46:47], v[52:53] op_sel_hi:[1,0]
	v_pk_mul_f32 v[40:41], v[40:41], v[52:53] op_sel_hi:[1,0]
	v_pk_mul_f32 v[42:43], v[42:43], v[52:53] op_sel_hi:[1,0]
	v_pk_mul_f32 v[36:37], v[36:37], v[52:53] op_sel_hi:[1,0]
	v_pk_mul_f32 v[38:39], v[38:39], v[52:53] op_sel_hi:[1,0]
	v_pk_mul_f32 v[32:33], v[32:33], v[52:53] op_sel_hi:[1,0]
	v_pk_mul_f32 v[34:35], v[34:35], v[52:53] op_sel_hi:[1,0]
	s_waitcnt lgkmcnt(0)
	v_pk_mul_f32 v[44:45], v[48:49], v[44:45]
	v_pk_mul_f32 v[46:47], v[50:51], v[46:47]
	v_cvt_pk_bf16_f32 v44, v44, v45
	s_nop 0
	v_cvt_pk_bf16_f32 v45, v46, v47
	global_store_dwordx2 v[54:55], v[44:45], off
	v_mov_b64_e32 v[44:45], v[208:209]
	v_mov_b64_e32 v[46:47], v[210:211]
	s_waitcnt lgkmcnt(0)
	v_pk_mul_f32 v[40:41], v[44:45], v[40:41]
	v_pk_mul_f32 v[42:43], v[46:47], v[42:43]
	v_cvt_pk_bf16_f32 v40, v40, v41
	s_nop 0
	v_cvt_pk_bf16_f32 v41, v42, v43
	global_store_dwordx2 v[54:55], v[40:41], off offset:32
	v_mov_b64_e32 v[40:41], v[212:213]
	v_mov_b64_e32 v[42:43], v[214:215]
	s_waitcnt lgkmcnt(0)
	v_pk_mul_f32 v[36:37], v[40:41], v[36:37]
	v_pk_mul_f32 v[38:39], v[42:43], v[38:39]
	v_cvt_pk_bf16_f32 v36, v36, v37
	s_nop 0
	v_cvt_pk_bf16_f32 v37, v38, v39
	global_store_dwordx2 v[54:55], v[36:37], off offset:64
	v_mov_b64_e32 v[36:37], v[216:217]
	v_mov_b64_e32 v[38:39], v[218:219]
	s_waitcnt lgkmcnt(0)
; __device__ __forceinline__ unsigned pk2(float lo, float hi) { return pg8::cvt_pk_bf16(lo, hi); }
; template <int NMT> __device__ __forceinline__ void ssd_out_item(const int ci, const int mt0, const float* DT, const bf16* XT, const bf16* BN, const bf16* CN, const bf16* HST, const bf16* Z, const float* ssd_norm, ...
;     ...
;         for (int mt = 0; mt < NMT; ++mt) { const int l = 16 * (mt0 + mt) + fr; float tot = 0.f;
; #pragma unroll
;             for (int w = 0; w < 8; ++w) tot += sSS[w * 64 + l];
;             const float rstd = rsqrtf(tot * (1.0f / 512.0f) + EPSN);
; #pragma unroll
;             for (int nt = 0; nt < 4; ++nt) { const f32x4 nw = *(const f32x4*)(ssd_norm + h * 64 + 16 * nt + 4 * fq); const f32x4 o = acc[nt][mt] * rstd * nw;
;                 v2u ow; ow.x = pk2(o[0], o[1]); ow.y = pk2(o[2], o[3]); *(v2u*)(MIXA + (size_t)(row0 + l) * 1024 + h * 64 + 16 * nt + 4 * fq) = ow; } }
;         __syncthreads();
	v_pk_mul_f32 v[34:35], v[34:35], v[38:39]
	v_pk_mul_f32 v[32:33], v[32:33], v[36:37]
	s_nop 0
	v_cvt_pk_bf16_f32 v32, v32, v33
	v_cvt_pk_bf16_f32 v33, v34, v35
	v_add_u32_e32 v34, 0x80, v83
	global_store_dwordx2 v[54:55], v[32:33], off offset:96
	ds_read2st64_b32 v[32:33], v34 offset0:152 offset1:153
	s_waitcnt lgkmcnt(0)
	v_add_f32_e32 v32, 0, v32
	v_add_f32_e32 v35, v32, v33
	ds_read2st64_b32 v[32:33], v34 offset0:154 offset1:155
	s_waitcnt lgkmcnt(0)
	v_add_f32_e32 v32, v35, v32
	v_add_f32_e32 v35, v32, v33
	ds_read2st64_b32 v[32:33], v34 offset0:156 offset1:157
	s_waitcnt lgkmcnt(0)
	v_add_f32_e32 v32, v35, v32
	v_add_f32_e32 v35, v32, v33
	ds_read2st64_b32 v[32:33], v34 offset0:158 offset1:159
	s_waitcnt lgkmcnt(0)
	v_add_f32_e32 v32, v35, v32
	v_add_f32_e32 v32, v32, v33
	v_fmamk_f32 v32, v32, 0x3b000000, v137
	v_cmp_gt_f32_e32 vcc, s62, v32
	v_mul_f32_e32 v33, 0x4b800000, v32
	s_nop 0
	v_cndmask_b32_e32 v32, v32, v33, vcc
	v_rsq_f32_e32 v32, v32
	s_nop 0
	v_mul_f32_e32 v33, 0x45800000, v32
	v_cndmask_b32_e32 v36, v32, v33, vcc
	v_lshlrev_b64 v[32:33], 11, v[100:101]
	v_lshl_add_u64 v[38:39], v[98:99], 0, v[32:33]
	v_mov_b64_e32 v[32:33], v[204:205]
	v_mov_b64_e32 v[34:35], v[206:207]
	v_pk_mul_f32 v[28:29], v[28:29], v[36:37] op_sel_hi:[1,0]
	v_pk_mul_f32 v[30:31], v[30:31], v[36:37] op_sel_hi:[1,0]
	v_pk_mul_f32 v[24:25], v[24:25], v[36:37] op_sel_hi:[1,0]
	v_pk_mul_f32 v[26:27], v[26:27], v[36:37] op_sel_hi:[1,0]
	v_pk_mul_f32 v[20:21], v[20:21], v[36:37] op_sel_hi:[1,0]
	v_pk_mul_f32 v[22:23], v[22:23], v[36:37] op_sel_hi:[1,0]
	v_pk_mul_f32 v[16:17], v[16:17], v[36:37] op_sel_hi:[1,0]
	v_pk_mul_f32 v[18:19], v[18:19], v[36:37] op_sel_hi:[1,0]
	s_waitcnt lgkmcnt(0)
	v_pk_mul_f32 v[28:29], v[32:33], v[28:29]
	v_pk_mul_f32 v[30:31], v[34:35], v[30:31]
	v_cvt_pk_bf16_f32 v28, v28, v29
	s_nop 0
	v_cvt_pk_bf16_f32 v29, v30, v31
	global_store_dwordx2 v[38:39], v[28:29], off
	v_mov_b64_e32 v[28:29], v[208:209]
	v_mov_b64_e32 v[30:31], v[210:211]
	s_waitcnt lgkmcnt(0)
	v_pk_mul_f32 v[24:25], v[28:29], v[24:25]
	v_pk_mul_f32 v[26:27], v[30:31], v[26:27]
	v_cvt_pk_bf16_f32 v24, v24, v25
	s_nop 0
	v_cvt_pk_bf16_f32 v25, v26, v27
	global_store_dwordx2 v[38:39], v[24:25], off offset:32
	v_mov_b64_e32 v[24:25], v[212:213]
	v_mov_b64_e32 v[26:27], v[214:215]
	s_waitcnt lgkmcnt(0)
	v_pk_mul_f32 v[20:21], v[24:25], v[20:21]
	v_pk_mul_f32 v[22:23], v[26:27], v[22:23]
	v_cvt_pk_bf16_f32 v20, v20, v21
	s_nop 0
	v_cvt_pk_bf16_f32 v21, v22, v23
	global_store_dwordx2 v[38:39], v[20:21], off offset:64
	v_mov_b64_e32 v[20:21], v[216:217]
	v_mov_b64_e32 v[22:23], v[218:219]
	s_waitcnt lgkmcnt(0)
	v_pk_mul_f32 v[16:17], v[16:17], v[20:21]
	v_pk_mul_f32 v[18:19], v[18:19], v[22:23]
	v_cvt_pk_bf16_f32 v16, v16, v17
	s_nop 0
	v_cvt_pk_bf16_f32 v17, v18, v19
	global_store_dwordx2 v[38:39], v[16:17], off offset:96
	ds_read2st64_b32 v[16:17], v84 offset0:152 offset1:153
	s_waitcnt lgkmcnt(0)
	v_add_f32_e32 v16, 0, v16
	v_add_f32_e32 v18, v16, v17
	ds_read2st64_b32 v[16:17], v84 offset0:154 offset1:155
	s_waitcnt lgkmcnt(0)
	v_add_f32_e32 v16, v18, v16
	v_add_f32_e32 v18, v16, v17
	ds_read2st64_b32 v[16:17], v84 offset0:156 offset1:157
	s_waitcnt lgkmcnt(0)
	v_add_f32_e32 v16, v18, v16
	v_add_f32_e32 v18, v16, v17
	ds_read2st64_b32 v[16:17], v84 offset0:158 offset1:159
	s_waitcnt lgkmcnt(0)
	v_add_f32_e32 v16, v18, v16
	v_add_f32_e32 v16, v16, v17
	v_fmamk_f32 v16, v16, 0x3b000000, v137
	v_cmp_gt_f32_e32 vcc, s62, v16
	v_mul_f32_e32 v17, 0x4b800000, v16
	s_nop 0
	v_cndmask_b32_e32 v16, v16, v17, vcc
	v_rsq_f32_e32 v16, v16
	s_nop 0
	v_mul_f32_e32 v17, 0x45800000, v16
	v_cndmask_b32_e32 v20, v16, v17, vcc
	v_lshlrev_b64 v[16:17], 11, v[106:107]
	v_lshl_add_u64 v[22:23], v[98:99], 0, v[16:17]
	v_mov_b64_e32 v[16:17], v[204:205]
	v_mov_b64_e32 v[18:19], v[206:207]
	v_pk_mul_f32 v[12:13], v[12:13], v[20:21] op_sel_hi:[1,0]
	v_pk_mul_f32 v[14:15], v[14:15], v[20:21] op_sel_hi:[1,0]
	v_pk_mul_f32 v[8:9], v[8:9], v[20:21] op_sel_hi:[1,0]
	v_pk_mul_f32 v[10:11], v[10:11], v[20:21] op_sel_hi:[1,0]
	v_pk_mul_f32 v[4:5], v[4:5], v[20:21] op_sel_hi:[1,0]
	v_pk_mul_f32 v[6:7], v[6:7], v[20:21] op_sel_hi:[1,0]
	v_pk_mul_f32 v[0:1], v[0:1], v[20:21] op_sel_hi:[1,0]
	v_pk_mul_f32 v[2:3], v[2:3], v[20:21] op_sel_hi:[1,0]
	s_waitcnt lgkmcnt(0)
	v_pk_mul_f32 v[12:13], v[16:17], v[12:13]
	v_pk_mul_f32 v[14:15], v[18:19], v[14:15]
	v_cvt_pk_bf16_f32 v12, v12, v13
	s_nop 0
	v_cvt_pk_bf16_f32 v13, v14, v15
	global_store_dwordx2 v[22:23], v[12:13], off
	v_mov_b64_e32 v[12:13], v[208:209]
	v_mov_b64_e32 v[14:15], v[210:211]
	s_waitcnt lgkmcnt(0)
	v_pk_mul_f32 v[8:9], v[12:13], v[8:9]
	v_pk_mul_f32 v[10:11], v[14:15], v[10:11]
	v_cvt_pk_bf16_f32 v8, v8, v9
	s_nop 0
	v_cvt_pk_bf16_f32 v9, v10, v11
	global_store_dwordx2 v[22:23], v[8:9], off offset:32
	v_mov_b64_e32 v[8:9], v[212:213]
	v_mov_b64_e32 v[10:11], v[214:215]
	s_waitcnt lgkmcnt(0)
	v_pk_mul_f32 v[4:5], v[8:9], v[4:5]
	v_pk_mul_f32 v[6:7], v[10:11], v[6:7]
	v_cvt_pk_bf16_f32 v4, v4, v5
	s_nop 0
	v_cvt_pk_bf16_f32 v5, v6, v7
	global_store_dwordx2 v[22:23], v[4:5], off offset:64
	v_mov_b64_e32 v[4:5], v[216:217]
	v_mov_b64_e32 v[6:7], v[218:219]
	s_waitcnt lgkmcnt(0)
	v_pk_mul_f32 v[0:1], v[0:1], v[4:5]
	v_pk_mul_f32 v[2:3], v[2:3], v[6:7]
	v_cvt_pk_bf16_f32 v0, v0, v1
	s_nop 0
	v_cvt_pk_bf16_f32 v1, v2, v3
	global_store_dwordx2 v[22:23], v[0:1], off offset:96
	s_barrier
	s_cbranch_scc1 .LBB0_1167
